# speedup vs baseline: 1.0032x; 1.0022x over previous
.LBB0_377:
	s_add_u32 s3, s16, 0xfff80080
	s_addc_u32 s18, s17, -1
	s_add_i32 s42, 0, 0x10000
	s_cmp_eq_u32 s41, 28
	s_cselect_b32 s21, s11, s18
	s_cselect_b32 s20, s31, s3
	v_add_u32_e32 v152, s42, v155
	s_cselect_b32 s19, s9, s40
	s_cselect_b32 s18, s34, s35
	s_add_i32 s3, 0, 0x14000
	ds_read_b128 v[140:143], v152
	ds_read_b128 v[144:147], v152 offset:1024
	ds_read_b128 v[148:151], v152 offset:2048
	ds_read_b128 v[158:161], v152 offset:3072
	v_add_u32_e32 v152, s3, v155
	ds_read_b128 v[162:165], v152
	ds_read_b128 v[166:169], v152 offset:1024
	ds_read_b128 v[170:173], v152 offset:2048
	ds_read_b128 v[174:177], v152 offset:3072
	v_lshl_add_u64 v[152:153], s[16:17], 0, v[136:137]
	s_add_i32 m0, s22, 0xc000
	ds_read_b128 v[188:191], v157
	ds_read_b128 v[192:195], v157 offset:1024
	ds_read_b128 v[196:199], v157 offset:2048
	ds_read_b128 v[200:203], v157 offset:3072
	ds_read_b128 v[204:207], v157 offset:4096
	ds_read_b128 v[218:221], v157 offset:5120
	ds_read_b128 v[222:225], v157 offset:6144
	ds_read_b128 v[226:229], v157 offset:7168
	global_load_lds_dwordx4 v[152:153], off
	v_lshl_add_u64 v[152:153], s[16:17], 0, v[138:139]
	s_add_i32 m0, s22, 0xe000
	s_nop 0
	global_load_lds_dwordx4 v[152:153], off
	s_waitcnt vmcnt(8)
	s_waitcnt lgkmcnt(0)
	s_waitcnt lgkmcnt(0)
	v_mfma_f32_16x16x32_bf16 v[126:129], v[140:143], v[188:191], v[126:129]
	v_mfma_f32_16x16x32_bf16 v[122:125], v[148:151], v[188:191], v[122:125]
	s_barrier
	s_setprio 1
	v_mfma_f32_16x16x32_bf16 v[110:113], v[140:143], v[196:199], v[110:113]
	v_mfma_f32_16x16x32_bf16 v[106:109], v[148:151], v[196:199], v[106:109]
	v_mfma_f32_16x16x32_bf16 v[94:97], v[140:143], v[204:207], v[94:97]
	v_mfma_f32_16x16x32_bf16 v[90:93], v[148:151], v[204:207], v[90:93]
	v_mfma_f32_16x16x32_bf16 v[78:81], v[140:143], v[222:225], v[78:81]
	v_mfma_f32_16x16x32_bf16 v[74:77], v[148:151], v[222:225], v[74:77]
	v_mfma_f32_16x16x32_bf16 v[126:129], v[144:147], v[192:195], v[126:129]
	v_mfma_f32_16x16x32_bf16 v[122:125], v[158:161], v[192:195], v[122:125]
	v_mfma_f32_16x16x32_bf16 v[110:113], v[144:147], v[200:203], v[110:113]
	v_mfma_f32_16x16x32_bf16 v[106:109], v[158:161], v[200:203], v[106:109]
	v_mfma_f32_16x16x32_bf16 v[94:97], v[144:147], v[218:221], v[94:97]
	v_mfma_f32_16x16x32_bf16 v[90:93], v[158:161], v[218:221], v[90:93]
	v_mfma_f32_16x16x32_bf16 v[78:81], v[144:147], v[226:229], v[78:81]
	v_mfma_f32_16x16x32_bf16 v[74:77], v[158:161], v[226:229], v[74:77]
	v_mfma_f32_16x16x32_bf16 v[118:121], v[162:165], v[188:191], v[118:121]
	v_mfma_f32_16x16x32_bf16 v[114:117], v[170:173], v[188:191], v[114:117]
	v_mfma_f32_16x16x32_bf16 v[102:105], v[162:165], v[196:199], v[102:105]
	v_mfma_f32_16x16x32_bf16 v[98:101], v[170:173], v[196:199], v[98:101]
	v_mfma_f32_16x16x32_bf16 v[86:89], v[162:165], v[204:207], v[86:89]
	v_mfma_f32_16x16x32_bf16 v[82:85], v[170:173], v[204:207], v[82:85]
	v_mfma_f32_16x16x32_bf16 v[70:73], v[162:165], v[222:225], v[70:73]
	v_mfma_f32_16x16x32_bf16 v[66:69], v[170:173], v[222:225], v[66:69]
	v_mfma_f32_16x16x32_bf16 v[118:121], v[166:169], v[192:195], v[118:121]
	v_mfma_f32_16x16x32_bf16 v[114:117], v[174:177], v[192:195], v[114:117]
	v_mfma_f32_16x16x32_bf16 v[102:105], v[166:169], v[200:203], v[102:105]
	v_mfma_f32_16x16x32_bf16 v[98:101], v[174:177], v[200:203], v[98:101]
	v_mfma_f32_16x16x32_bf16 v[86:89], v[166:169], v[218:221], v[86:89]
	v_mfma_f32_16x16x32_bf16 v[82:85], v[174:177], v[218:221], v[82:85]
	v_mfma_f32_16x16x32_bf16 v[70:73], v[166:169], v[226:229], v[70:73]
	v_mfma_f32_16x16x32_bf16 v[66:69], v[174:177], v[226:229], v[66:69]
	s_setprio 0
	s_barrier
	s_add_i32 s42, s42, s2
	v_lshl_add_u64 v[152:153], s[18:19], 0, v[0:1]
	s_mov_b32 m0, s42
	ds_read_b128 v[188:191], v157 offset:16384
	ds_read_b128 v[192:195], v157 offset:17408
	ds_read_b128 v[196:199], v157 offset:18432
	ds_read_b128 v[200:203], v157 offset:19456
	ds_read_b128 v[204:207], v157 offset:20480
	ds_read_b128 v[218:221], v157 offset:21504
	ds_read_b128 v[222:225], v157 offset:22528
	ds_read_b128 v[226:229], v157 offset:23552
	global_load_lds_dwordx4 v[152:153], off
	s_add_i32 m0, s42, 0x2000
	s_add_u32 s44, s18, 0x80000
	v_lshl_add_u64 v[178:179], s[18:19], 0, v[130:131]
	s_addc_u32 s45, s19, 0
	s_add_i32 s3, s3, s2
	global_load_lds_dwordx4 v[178:179], off
	v_lshl_add_u64 v[180:181], s[44:45], 0, v[0:1]
	s_mov_b32 m0, s3
	v_lshl_add_u64 v[182:183], s[20:21], 0, v[132:133]
	global_load_lds_dwordx4 v[180:181], off
	v_lshl_add_u64 v[180:181], s[44:45], 0, v[130:131]
	s_add_i32 m0, s3, 0x2000
	s_nop 0
	global_load_lds_dwordx4 v[180:181], off
	v_lshl_add_u64 v[180:181], s[20:21], 0, v[134:135]
	s_mov_b32 m0, s22
	s_nop 0
	global_load_lds_dwordx4 v[180:181], off
	s_mov_b32 m0, s23
	s_nop 0
	global_load_lds_dwordx4 v[182:183], off
	s_waitcnt vmcnt(8)
	s_waitcnt lgkmcnt(0)
	s_waitcnt lgkmcnt(0)
	v_mfma_f32_16x16x32_bf16 v[62:65], v[140:143], v[188:191], v[62:65]
	v_mfma_f32_16x16x32_bf16 v[58:61], v[148:151], v[188:191], v[58:61]
	s_barrier
	s_setprio 1
	v_mfma_f32_16x16x32_bf16 v[46:49], v[140:143], v[196:199], v[46:49]
	v_mfma_f32_16x16x32_bf16 v[42:45], v[148:151], v[196:199], v[42:45]
	v_mfma_f32_16x16x32_bf16 v[30:33], v[140:143], v[204:207], v[30:33]
	v_mfma_f32_16x16x32_bf16 v[26:29], v[148:151], v[204:207], v[26:29]
	v_mfma_f32_16x16x32_bf16 v[14:17], v[140:143], v[222:225], v[14:17]
	v_mfma_f32_16x16x32_bf16 v[6:9], v[148:151], v[222:225], v[6:9]
	v_mfma_f32_16x16x32_bf16 v[62:65], v[144:147], v[192:195], v[62:65]
	v_mfma_f32_16x16x32_bf16 v[58:61], v[158:161], v[192:195], v[58:61]
	v_mfma_f32_16x16x32_bf16 v[46:49], v[144:147], v[200:203], v[46:49]
	v_mfma_f32_16x16x32_bf16 v[42:45], v[158:161], v[200:203], v[42:45]
	v_mfma_f32_16x16x32_bf16 v[30:33], v[144:147], v[218:221], v[30:33]
	v_mfma_f32_16x16x32_bf16 v[26:29], v[158:161], v[218:221], v[26:29]
	v_mfma_f32_16x16x32_bf16 v[14:17], v[144:147], v[226:229], v[14:17]
	v_mfma_f32_16x16x32_bf16 v[6:9], v[158:161], v[226:229], v[6:9]
	v_mfma_f32_16x16x32_bf16 v[54:57], v[162:165], v[188:191], v[54:57]
	v_mfma_f32_16x16x32_bf16 v[50:53], v[170:173], v[188:191], v[50:53]
	v_mfma_f32_16x16x32_bf16 v[38:41], v[162:165], v[196:199], v[38:41]
	v_mfma_f32_16x16x32_bf16 v[34:37], v[170:173], v[196:199], v[34:37]
	v_mfma_f32_16x16x32_bf16 v[22:25], v[162:165], v[204:207], v[22:25]
	v_mfma_f32_16x16x32_bf16 v[18:21], v[170:173], v[204:207], v[18:21]
	v_mfma_f32_16x16x32_bf16 v[10:13], v[162:165], v[222:225], v[10:13]
	v_mfma_f32_16x16x32_bf16 v[2:5], v[170:173], v[222:225], v[2:5]
	v_mfma_f32_16x16x32_bf16 v[54:57], v[166:169], v[192:195], v[54:57]
	v_mfma_f32_16x16x32_bf16 v[50:53], v[174:177], v[192:195], v[50:53]
	v_mfma_f32_16x16x32_bf16 v[38:41], v[166:169], v[200:203], v[38:41]
	v_mfma_f32_16x16x32_bf16 v[34:37], v[174:177], v[200:203], v[34:37]
	v_mfma_f32_16x16x32_bf16 v[22:25], v[166:169], v[218:221], v[22:25]
	v_mfma_f32_16x16x32_bf16 v[18:21], v[174:177], v[218:221], v[18:21]
	v_mfma_f32_16x16x32_bf16 v[10:13], v[166:169], v[226:229], v[10:13]
	v_mfma_f32_16x16x32_bf16 v[2:5], v[174:177], v[226:229], v[2:5]
	s_setprio 0
	s_barrier
	s_add_i32 s3, 0, 0x18000
	s_add_i32 s42, 0, 0x1c000
	v_add_u32_e32 v158, s3, v155
	v_add_u32_e32 v174, s42, v155
	ds_read_b128 v[140:143], v158
	ds_read_b128 v[144:147], v158 offset:1024
	ds_read_b128 v[148:151], v158 offset:2048
	ds_read_b128 v[158:161], v158 offset:3072
	ds_read_b128 v[162:165], v174
	ds_read_b128 v[166:169], v174 offset:1024
	ds_read_b128 v[170:173], v174 offset:2048
	ds_read_b128 v[174:177], v174 offset:3072
	s_add_u32 s20, s20, 0x80000
	s_addc_u32 s21, s21, 0
	s_mov_b32 m0, s24
	v_lshl_add_u64 v[184:185], s[20:21], 0, v[134:135]
	ds_read_b128 v[188:191], v157 offset:32768
	ds_read_b128 v[192:195], v157 offset:33792
	ds_read_b128 v[196:199], v157 offset:34816
	ds_read_b128 v[200:203], v157 offset:35840
	ds_read_b128 v[204:207], v157 offset:36864
	ds_read_b128 v[218:221], v157 offset:37888
	ds_read_b128 v[222:225], v157 offset:38912
	ds_read_b128 v[226:229], v157 offset:39936
	global_load_lds_dwordx4 v[184:185], off
	v_lshl_add_u64 v[184:185], s[20:21], 0, v[132:133]
	s_mov_b32 m0, s25
	s_nop 0
	global_load_lds_dwordx4 v[184:185], off
	s_waitcnt vmcnt(8)
	s_waitcnt lgkmcnt(0)
	s_waitcnt lgkmcnt(0)
	v_mfma_f32_16x16x32_bf16 v[126:129], v[140:143], v[188:191], v[126:129]
	v_mfma_f32_16x16x32_bf16 v[122:125], v[148:151], v[188:191], v[122:125]
	s_barrier
	s_setprio 1
	v_mfma_f32_16x16x32_bf16 v[110:113], v[140:143], v[196:199], v[110:113]
	v_mfma_f32_16x16x32_bf16 v[106:109], v[148:151], v[196:199], v[106:109]
	v_mfma_f32_16x16x32_bf16 v[94:97], v[140:143], v[204:207], v[94:97]
	v_mfma_f32_16x16x32_bf16 v[90:93], v[148:151], v[204:207], v[90:93]
	v_mfma_f32_16x16x32_bf16 v[78:81], v[140:143], v[222:225], v[78:81]
	v_mfma_f32_16x16x32_bf16 v[74:77], v[148:151], v[222:225], v[74:77]
	v_mfma_f32_16x16x32_bf16 v[126:129], v[144:147], v[192:195], v[126:129]
	v_mfma_f32_16x16x32_bf16 v[122:125], v[158:161], v[192:195], v[122:125]
	v_mfma_f32_16x16x32_bf16 v[110:113], v[144:147], v[200:203], v[110:113]
	v_mfma_f32_16x16x32_bf16 v[106:109], v[158:161], v[200:203], v[106:109]
	v_mfma_f32_16x16x32_bf16 v[94:97], v[144:147], v[218:221], v[94:97]
	v_mfma_f32_16x16x32_bf16 v[90:93], v[158:161], v[218:221], v[90:93]
	v_mfma_f32_16x16x32_bf16 v[78:81], v[144:147], v[226:229], v[78:81]
	v_mfma_f32_16x16x32_bf16 v[74:77], v[158:161], v[226:229], v[74:77]
	v_mfma_f32_16x16x32_bf16 v[118:121], v[162:165], v[188:191], v[118:121]
	v_mfma_f32_16x16x32_bf16 v[114:117], v[170:173], v[188:191], v[114:117]
	v_mfma_f32_16x16x32_bf16 v[102:105], v[162:165], v[196:199], v[102:105]
	v_mfma_f32_16x16x32_bf16 v[98:101], v[170:173], v[196:199], v[98:101]
	v_mfma_f32_16x16x32_bf16 v[86:89], v[162:165], v[204:207], v[86:89]
	v_mfma_f32_16x16x32_bf16 v[82:85], v[170:173], v[204:207], v[82:85]
	v_mfma_f32_16x16x32_bf16 v[70:73], v[162:165], v[222:225], v[70:73]
	v_mfma_f32_16x16x32_bf16 v[66:69], v[170:173], v[222:225], v[66:69]
	v_mfma_f32_16x16x32_bf16 v[118:121], v[166:169], v[192:195], v[118:121]
	v_mfma_f32_16x16x32_bf16 v[114:117], v[174:177], v[192:195], v[114:117]
	v_mfma_f32_16x16x32_bf16 v[102:105], v[166:169], v[200:203], v[102:105]
	v_mfma_f32_16x16x32_bf16 v[98:101], v[174:177], v[200:203], v[98:101]
	v_mfma_f32_16x16x32_bf16 v[86:89], v[166:169], v[218:221], v[86:89]
	v_mfma_f32_16x16x32_bf16 v[82:85], v[174:177], v[218:221], v[82:85]
	v_mfma_f32_16x16x32_bf16 v[70:73], v[166:169], v[226:229], v[70:73]
	v_mfma_f32_16x16x32_bf16 v[66:69], v[174:177], v[226:229], v[66:69]
	s_setprio 0
	s_barrier
	s_add_i32 s3, s3, s2
	v_lshl_add_u64 v[152:153], v[152:153], 0, s[52:53]
	s_mov_b32 m0, s3
	ds_read_b128 v[188:191], v157 offset:49152
	ds_read_b128 v[192:195], v157 offset:50176
	ds_read_b128 v[196:199], v157 offset:51200
	ds_read_b128 v[200:203], v157 offset:52224
	ds_read_b128 v[204:207], v157 offset:53248
	ds_read_b128 v[218:221], v157 offset:54272
	ds_read_b128 v[222:225], v157 offset:55296
	ds_read_b128 v[226:229], v157 offset:56320
	global_load_lds_dwordx4 v[152:153], off
	s_add_i32 m0, s3, 0x2000
	s_add_u32 s18, s18, 0x80080
	v_lshl_add_u64 v[152:153], v[178:179], 0, s[52:53]
	s_addc_u32 s19, s19, 0
	s_add_i32 s3, s42, s2
	global_load_lds_dwordx4 v[152:153], off
	v_lshl_add_u64 v[152:153], s[18:19], 0, v[0:1]
	s_mov_b32 m0, s3
	s_nop 0
	global_load_lds_dwordx4 v[152:153], off
	v_lshl_add_u64 v[152:153], s[18:19], 0, v[130:131]
	s_add_i32 m0, s3, 0x2000
	s_nop 0
	global_load_lds_dwordx4 v[152:153], off
	v_lshl_add_u64 v[152:153], v[180:181], 0, s[52:53]
	s_mov_b32 m0, s26
	s_nop 0
	global_load_lds_dwordx4 v[152:153], off
	v_lshl_add_u64 v[152:153], v[182:183], 0, s[52:53]
	s_mov_b32 m0, s27
	s_nop 0
	global_load_lds_dwordx4 v[152:153], off
	s_waitcnt vmcnt(8)
	s_waitcnt lgkmcnt(0)
	s_waitcnt lgkmcnt(0)
	v_mfma_f32_16x16x32_bf16 v[62:65], v[140:143], v[188:191], v[62:65]
	v_mfma_f32_16x16x32_bf16 v[58:61], v[148:151], v[188:191], v[58:61]
	s_barrier
	s_setprio 1
	v_mfma_f32_16x16x32_bf16 v[46:49], v[140:143], v[196:199], v[46:49]
	v_mfma_f32_16x16x32_bf16 v[42:45], v[148:151], v[196:199], v[42:45]
	v_mfma_f32_16x16x32_bf16 v[30:33], v[140:143], v[204:207], v[30:33]
	v_mfma_f32_16x16x32_bf16 v[26:29], v[148:151], v[204:207], v[26:29]
	v_mfma_f32_16x16x32_bf16 v[14:17], v[140:143], v[222:225], v[14:17]
	v_mfma_f32_16x16x32_bf16 v[6:9], v[148:151], v[222:225], v[6:9]
	v_mfma_f32_16x16x32_bf16 v[62:65], v[144:147], v[192:195], v[62:65]
	v_mfma_f32_16x16x32_bf16 v[58:61], v[158:161], v[192:195], v[58:61]
	v_mfma_f32_16x16x32_bf16 v[46:49], v[144:147], v[200:203], v[46:49]
	v_mfma_f32_16x16x32_bf16 v[42:45], v[158:161], v[200:203], v[42:45]
	v_mfma_f32_16x16x32_bf16 v[30:33], v[144:147], v[218:221], v[30:33]
	v_mfma_f32_16x16x32_bf16 v[26:29], v[158:161], v[218:221], v[26:29]
	v_mfma_f32_16x16x32_bf16 v[14:17], v[144:147], v[226:229], v[14:17]
	v_mfma_f32_16x16x32_bf16 v[6:9], v[158:161], v[226:229], v[6:9]
	v_mfma_f32_16x16x32_bf16 v[54:57], v[162:165], v[188:191], v[54:57]
	v_mfma_f32_16x16x32_bf16 v[50:53], v[170:173], v[188:191], v[50:53]
	v_mfma_f32_16x16x32_bf16 v[38:41], v[162:165], v[196:199], v[38:41]
	v_mfma_f32_16x16x32_bf16 v[34:37], v[170:173], v[196:199], v[34:37]
	v_mfma_f32_16x16x32_bf16 v[22:25], v[162:165], v[204:207], v[22:25]
	v_mfma_f32_16x16x32_bf16 v[18:21], v[170:173], v[204:207], v[18:21]
	v_mfma_f32_16x16x32_bf16 v[10:13], v[162:165], v[222:225], v[10:13]
	v_mfma_f32_16x16x32_bf16 v[2:5], v[170:173], v[222:225], v[2:5]
	v_mfma_f32_16x16x32_bf16 v[54:57], v[166:169], v[192:195], v[54:57]
	v_mfma_f32_16x16x32_bf16 v[50:53], v[174:177], v[192:195], v[50:53]
	v_mfma_f32_16x16x32_bf16 v[38:41], v[166:169], v[200:203], v[38:41]
	v_mfma_f32_16x16x32_bf16 v[34:37], v[174:177], v[200:203], v[34:37]
	v_mfma_f32_16x16x32_bf16 v[22:25], v[166:169], v[218:221], v[22:25]
	v_mfma_f32_16x16x32_bf16 v[18:21], v[174:177], v[218:221], v[18:21]
	v_mfma_f32_16x16x32_bf16 v[10:13], v[166:169], v[226:229], v[10:13]
	v_mfma_f32_16x16x32_bf16 v[2:5], v[174:177], v[226:229], v[2:5]
	s_setprio 0
	s_barrier
	s_add_i32 s41, s41, 2
	s_add_u32 s16, s16, 0x100
	s_addc_u32 s17, s17, 0
	s_add_u32 s35, s35, 0x100
	s_addc_u32 s40, s40, 0
	s_cmp_gt_u32 s41, 29
	s_cbranch_scc0 .LBB0_377
	s_and_b64 vcc, exec, s[6:7]
	s_movk_i32 s40, 0x4000
	s_movk_i32 s41, 0x6000
	s_cbranch_vccz .LBB0_380
	s_barrier

.LBB0_399:
	s_add_u32 s3, s0, 0xfff80080
	s_addc_u32 s4, s1, -1
	s_add_i32 s42, 0, 0x10000
	s_cmp_eq_u32 s46, 28
	s_cselect_b32 s7, s8, s4
	s_cselect_b32 s6, s9, s3
	v_add_u32_e32 v0, s42, v206
	s_cselect_b32 s5, s19, s27
	s_cselect_b32 s4, s21, s26
	s_add_i32 s3, 0, 0x14000
	ds_read_b128 v[130:133], v0
	ds_read_b128 v[134:137], v0 offset:1024
	ds_read_b128 v[138:141], v0 offset:2048
	ds_read_b128 v[142:145], v0 offset:3072
	v_add_u32_e32 v0, s3, v206
	ds_read_b128 v[146:149], v0
	ds_read_b128 v[150:153], v0 offset:1024
	s_waitcnt lgkmcnt(0)
	ds_read_b128 v[154:157], v0 offset:2048
	ds_read_b128 v[158:161], v0 offset:3072
	v_lshl_add_u64 v[176:177], s[0:1], 0, v[170:171]
	s_add_i32 m0, s28, 0xc000
	ds_read_b128 v[196:199], v218
	ds_read_b128 v[200:203], v218 offset:1024
	ds_read_b128 v[220:223], v218 offset:2048
	ds_read_b128 v[224:227], v218 offset:3072
	ds_read_b128 v[228:231], v218 offset:4096
	ds_read_b128 v[232:235], v218 offset:5120
	ds_read_b128 v[236:239], v218 offset:6144
	ds_read_b128 v[240:243], v218 offset:7168
	global_load_lds_dwordx4 v[176:177], off
	v_lshl_add_u64 v[176:177], s[0:1], 0, v[172:173]
	s_add_i32 m0, s28, 0xe000
	s_nop 0
	global_load_lds_dwordx4 v[176:177], off
	s_waitcnt vmcnt(8)
	s_waitcnt lgkmcnt(0)
	s_waitcnt lgkmcnt(0)
	v_mfma_f32_16x16x32_bf16 v[126:129], v[130:133], v[196:199], v[126:129]
	v_mfma_f32_16x16x32_bf16 v[122:125], v[138:141], v[196:199], v[122:125]
	s_barrier
	s_setprio 1
	v_mfma_f32_16x16x32_bf16 v[118:121], v[130:133], v[220:223], v[118:121]
	v_mfma_f32_16x16x32_bf16 v[114:117], v[138:141], v[220:223], v[114:117]
	v_mfma_f32_16x16x32_bf16 v[110:113], v[130:133], v[228:231], v[110:113]
	v_mfma_f32_16x16x32_bf16 v[106:109], v[138:141], v[228:231], v[106:109]
	v_mfma_f32_16x16x32_bf16 v[102:105], v[130:133], v[236:239], v[102:105]
	v_mfma_f32_16x16x32_bf16 v[98:101], v[138:141], v[236:239], v[98:101]
	v_mfma_f32_16x16x32_bf16 v[126:129], v[134:137], v[200:203], v[126:129]
	v_mfma_f32_16x16x32_bf16 v[122:125], v[142:145], v[200:203], v[122:125]
	v_mfma_f32_16x16x32_bf16 v[118:121], v[134:137], v[224:227], v[118:121]
	v_mfma_f32_16x16x32_bf16 v[114:117], v[142:145], v[224:227], v[114:117]
	v_mfma_f32_16x16x32_bf16 v[110:113], v[134:137], v[232:235], v[110:113]
	v_mfma_f32_16x16x32_bf16 v[106:109], v[142:145], v[232:235], v[106:109]
	v_mfma_f32_16x16x32_bf16 v[102:105], v[134:137], v[240:243], v[102:105]
	v_mfma_f32_16x16x32_bf16 v[98:101], v[142:145], v[240:243], v[98:101]
	v_mfma_f32_16x16x32_bf16 v[94:97], v[146:149], v[196:199], v[94:97]
	v_mfma_f32_16x16x32_bf16 v[90:93], v[154:157], v[196:199], v[90:93]
	v_mfma_f32_16x16x32_bf16 v[86:89], v[146:149], v[220:223], v[86:89]
	v_mfma_f32_16x16x32_bf16 v[82:85], v[154:157], v[220:223], v[82:85]
	v_mfma_f32_16x16x32_bf16 v[78:81], v[146:149], v[228:231], v[78:81]
	v_mfma_f32_16x16x32_bf16 v[74:77], v[154:157], v[228:231], v[74:77]
	v_mfma_f32_16x16x32_bf16 v[70:73], v[146:149], v[236:239], v[70:73]
	v_mfma_f32_16x16x32_bf16 v[66:69], v[154:157], v[236:239], v[66:69]
	v_mfma_f32_16x16x32_bf16 v[94:97], v[150:153], v[200:203], v[94:97]
	v_mfma_f32_16x16x32_bf16 v[90:93], v[158:161], v[200:203], v[90:93]
	v_mfma_f32_16x16x32_bf16 v[86:89], v[150:153], v[224:227], v[86:89]
	v_mfma_f32_16x16x32_bf16 v[82:85], v[158:161], v[224:227], v[82:85]
	v_mfma_f32_16x16x32_bf16 v[78:81], v[150:153], v[232:235], v[78:81]
	v_mfma_f32_16x16x32_bf16 v[74:77], v[158:161], v[232:235], v[74:77]
	v_mfma_f32_16x16x32_bf16 v[70:73], v[150:153], v[240:243], v[70:73]
	v_mfma_f32_16x16x32_bf16 v[66:69], v[158:161], v[240:243], v[66:69]
	s_setprio 0
	s_barrier
	s_add_i32 s42, s42, s2
	v_lshl_add_u64 v[176:177], s[4:5], 0, v[166:167]
	s_mov_b32 m0, s42
	ds_read_b128 v[196:199], v218 offset:16384
	ds_read_b128 v[200:203], v218 offset:17408
	ds_read_b128 v[220:223], v218 offset:18432
	ds_read_b128 v[224:227], v218 offset:19456
	ds_read_b128 v[228:231], v218 offset:20480
	ds_read_b128 v[232:235], v218 offset:21504
	ds_read_b128 v[236:239], v218 offset:22528
	ds_read_b128 v[240:243], v218 offset:23552
	global_load_lds_dwordx4 v[176:177], off
	s_add_i32 m0, s42, 0x2000
	s_add_u32 s56, s4, 0x80000
	v_lshl_add_u64 v[178:179], s[4:5], 0, v[162:163]
	s_addc_u32 s57, s5, 0
	s_add_i32 s3, s3, s2
	global_load_lds_dwordx4 v[178:179], off
	v_lshl_add_u64 v[244:245], s[56:57], 0, v[166:167]
	s_mov_b32 m0, s3
	v_lshl_add_u64 v[246:247], s[6:7], 0, v[164:165]
	global_load_lds_dwordx4 v[244:245], off
	v_lshl_add_u64 v[244:245], s[56:57], 0, v[162:163]
	s_add_i32 m0, s3, 0x2000
	s_nop 0
	global_load_lds_dwordx4 v[244:245], off
	v_lshl_add_u64 v[244:245], s[6:7], 0, v[168:169]
	s_mov_b32 m0, s28
	s_nop 0
	global_load_lds_dwordx4 v[244:245], off
	s_mov_b32 m0, s29
	s_nop 0
	global_load_lds_dwordx4 v[246:247], off
	s_waitcnt vmcnt(8)
	s_waitcnt lgkmcnt(0)
	s_waitcnt lgkmcnt(0)
	v_mfma_f32_16x16x32_bf16 v[62:65], v[130:133], v[196:199], v[62:65]
	v_mfma_f32_16x16x32_bf16 v[58:61], v[138:141], v[196:199], v[58:61]
	s_barrier
	s_setprio 1
	v_mfma_f32_16x16x32_bf16 v[54:57], v[130:133], v[220:223], v[54:57]
	v_mfma_f32_16x16x32_bf16 v[50:53], v[138:141], v[220:223], v[50:53]
	v_mfma_f32_16x16x32_bf16 v[46:49], v[130:133], v[228:231], v[46:49]
	v_mfma_f32_16x16x32_bf16 v[42:45], v[138:141], v[228:231], v[42:45]
	v_mfma_f32_16x16x32_bf16 v[38:41], v[130:133], v[236:239], v[38:41]
	v_mfma_f32_16x16x32_bf16 v[34:37], v[138:141], v[236:239], v[34:37]
	v_mfma_f32_16x16x32_bf16 v[62:65], v[134:137], v[200:203], v[62:65]
	v_mfma_f32_16x16x32_bf16 v[58:61], v[142:145], v[200:203], v[58:61]
	v_mfma_f32_16x16x32_bf16 v[54:57], v[134:137], v[224:227], v[54:57]
	v_mfma_f32_16x16x32_bf16 v[50:53], v[142:145], v[224:227], v[50:53]
	v_mfma_f32_16x16x32_bf16 v[46:49], v[134:137], v[232:235], v[46:49]
	v_mfma_f32_16x16x32_bf16 v[42:45], v[142:145], v[232:235], v[42:45]
	v_mfma_f32_16x16x32_bf16 v[38:41], v[134:137], v[240:243], v[38:41]
	v_mfma_f32_16x16x32_bf16 v[34:37], v[142:145], v[240:243], v[34:37]
	v_mfma_f32_16x16x32_bf16 v[30:33], v[146:149], v[196:199], v[30:33]
	v_mfma_f32_16x16x32_bf16 v[26:29], v[154:157], v[196:199], v[26:29]
	v_mfma_f32_16x16x32_bf16 v[22:25], v[146:149], v[220:223], v[22:25]
	v_mfma_f32_16x16x32_bf16 v[18:21], v[154:157], v[220:223], v[18:21]
	v_mfma_f32_16x16x32_bf16 v[14:17], v[146:149], v[228:231], v[14:17]
	v_mfma_f32_16x16x32_bf16 v[10:13], v[154:157], v[228:231], v[10:13]
	v_mfma_f32_16x16x32_bf16 v[6:9], v[146:149], v[236:239], v[6:9]
	v_mfma_f32_16x16x32_bf16 v[2:5], v[154:157], v[236:239], v[2:5]
	v_mfma_f32_16x16x32_bf16 v[30:33], v[150:153], v[200:203], v[30:33]
	v_mfma_f32_16x16x32_bf16 v[26:29], v[158:161], v[200:203], v[26:29]
	v_mfma_f32_16x16x32_bf16 v[22:25], v[150:153], v[224:227], v[22:25]
	v_mfma_f32_16x16x32_bf16 v[18:21], v[158:161], v[224:227], v[18:21]
	v_mfma_f32_16x16x32_bf16 v[14:17], v[150:153], v[232:235], v[14:17]
	v_mfma_f32_16x16x32_bf16 v[10:13], v[158:161], v[232:235], v[10:13]
	v_mfma_f32_16x16x32_bf16 v[6:9], v[150:153], v[240:243], v[6:9]
	v_mfma_f32_16x16x32_bf16 v[2:5], v[158:161], v[240:243], v[2:5]
	s_setprio 0
	s_barrier
	s_add_i32 s3, 0, 0x18000
	v_add_u32_e32 v0, s3, v206
	s_add_i32 s42, 0, 0x1c000
	ds_read_b128 v[130:133], v0
	ds_read_b128 v[134:137], v0 offset:1024
	ds_read_b128 v[138:141], v0 offset:2048
	ds_read_b128 v[142:145], v0 offset:3072
	v_add_u32_e32 v0, s42, v206
	ds_read_b128 v[146:149], v0
	ds_read_b128 v[150:153], v0 offset:1024
	ds_read_b128 v[154:157], v0 offset:2048
	ds_read_b128 v[158:161], v0 offset:3072
	s_add_u32 s6, s6, 0x80000
	s_addc_u32 s7, s7, 0
	s_mov_b32 m0, s30
	v_lshl_add_u64 v[248:249], s[6:7], 0, v[168:169]
	ds_read_b128 v[196:199], v218 offset:32768
	ds_read_b128 v[200:203], v218 offset:33792
	ds_read_b128 v[220:223], v218 offset:34816
	ds_read_b128 v[224:227], v218 offset:35840
	ds_read_b128 v[228:231], v218 offset:36864
	ds_read_b128 v[232:235], v218 offset:37888
	ds_read_b128 v[236:239], v218 offset:38912
	ds_read_b128 v[240:243], v218 offset:39936
	global_load_lds_dwordx4 v[248:249], off
	v_lshl_add_u64 v[248:249], s[6:7], 0, v[164:165]
	s_mov_b32 m0, s31
	s_nop 0
	global_load_lds_dwordx4 v[248:249], off
	s_waitcnt vmcnt(8)
	s_waitcnt lgkmcnt(0)
	s_waitcnt lgkmcnt(0)
	v_mfma_f32_16x16x32_bf16 v[126:129], v[130:133], v[196:199], v[126:129]
	v_mfma_f32_16x16x32_bf16 v[122:125], v[138:141], v[196:199], v[122:125]
	s_barrier
	s_setprio 1
	v_mfma_f32_16x16x32_bf16 v[118:121], v[130:133], v[220:223], v[118:121]
	v_mfma_f32_16x16x32_bf16 v[114:117], v[138:141], v[220:223], v[114:117]
	v_mfma_f32_16x16x32_bf16 v[110:113], v[130:133], v[228:231], v[110:113]
	v_mfma_f32_16x16x32_bf16 v[106:109], v[138:141], v[228:231], v[106:109]
	v_mfma_f32_16x16x32_bf16 v[102:105], v[130:133], v[236:239], v[102:105]
	v_mfma_f32_16x16x32_bf16 v[98:101], v[138:141], v[236:239], v[98:101]
	v_mfma_f32_16x16x32_bf16 v[126:129], v[134:137], v[200:203], v[126:129]
	v_mfma_f32_16x16x32_bf16 v[122:125], v[142:145], v[200:203], v[122:125]
	v_mfma_f32_16x16x32_bf16 v[118:121], v[134:137], v[224:227], v[118:121]
	v_mfma_f32_16x16x32_bf16 v[114:117], v[142:145], v[224:227], v[114:117]
	v_mfma_f32_16x16x32_bf16 v[110:113], v[134:137], v[232:235], v[110:113]
	v_mfma_f32_16x16x32_bf16 v[106:109], v[142:145], v[232:235], v[106:109]
	v_mfma_f32_16x16x32_bf16 v[102:105], v[134:137], v[240:243], v[102:105]
	v_mfma_f32_16x16x32_bf16 v[98:101], v[142:145], v[240:243], v[98:101]
	v_mfma_f32_16x16x32_bf16 v[94:97], v[146:149], v[196:199], v[94:97]
	v_mfma_f32_16x16x32_bf16 v[90:93], v[154:157], v[196:199], v[90:93]
	v_mfma_f32_16x16x32_bf16 v[86:89], v[146:149], v[220:223], v[86:89]
	v_mfma_f32_16x16x32_bf16 v[82:85], v[154:157], v[220:223], v[82:85]
	v_mfma_f32_16x16x32_bf16 v[78:81], v[146:149], v[228:231], v[78:81]
	v_mfma_f32_16x16x32_bf16 v[74:77], v[154:157], v[228:231], v[74:77]
	v_mfma_f32_16x16x32_bf16 v[70:73], v[146:149], v[236:239], v[70:73]
	v_mfma_f32_16x16x32_bf16 v[66:69], v[154:157], v[236:239], v[66:69]
	v_mfma_f32_16x16x32_bf16 v[94:97], v[150:153], v[200:203], v[94:97]
	v_mfma_f32_16x16x32_bf16 v[90:93], v[158:161], v[200:203], v[90:93]
	v_mfma_f32_16x16x32_bf16 v[86:89], v[150:153], v[224:227], v[86:89]
	v_mfma_f32_16x16x32_bf16 v[82:85], v[158:161], v[224:227], v[82:85]
	v_mfma_f32_16x16x32_bf16 v[78:81], v[150:153], v[232:235], v[78:81]
	v_mfma_f32_16x16x32_bf16 v[74:77], v[158:161], v[232:235], v[74:77]
	v_mfma_f32_16x16x32_bf16 v[70:73], v[150:153], v[240:243], v[70:73]
	v_mfma_f32_16x16x32_bf16 v[66:69], v[158:161], v[240:243], v[66:69]
	s_setprio 0
	s_barrier
	s_add_i32 s3, s3, s2
	v_lshl_add_u64 v[176:177], v[176:177], 0, s[52:53]
	s_mov_b32 m0, s3
	ds_read_b128 v[196:199], v218 offset:49152
	ds_read_b128 v[200:203], v218 offset:50176
	ds_read_b128 v[220:223], v218 offset:51200
	ds_read_b128 v[224:227], v218 offset:52224
	ds_read_b128 v[228:231], v218 offset:53248
	ds_read_b128 v[232:235], v218 offset:54272
	ds_read_b128 v[236:239], v218 offset:55296
	ds_read_b128 v[240:243], v218 offset:56320
	global_load_lds_dwordx4 v[176:177], off
	s_add_i32 m0, s3, 0x2000
	s_add_u32 s4, s4, 0x80080
	v_lshl_add_u64 v[176:177], v[178:179], 0, s[52:53]
	s_addc_u32 s5, s5, 0
	s_add_i32 s3, s42, s2
	global_load_lds_dwordx4 v[176:177], off
	v_lshl_add_u64 v[176:177], s[4:5], 0, v[166:167]
	s_mov_b32 m0, s3
	s_nop 0
	global_load_lds_dwordx4 v[176:177], off
	v_lshl_add_u64 v[176:177], s[4:5], 0, v[162:163]
	s_add_i32 m0, s3, 0x2000
	s_nop 0
	global_load_lds_dwordx4 v[176:177], off
	v_lshl_add_u64 v[176:177], v[244:245], 0, s[52:53]
	s_mov_b32 m0, s35
	s_nop 0
	global_load_lds_dwordx4 v[176:177], off
	v_lshl_add_u64 v[176:177], v[246:247], 0, s[52:53]
	s_mov_b32 m0, s40
	s_nop 0
	global_load_lds_dwordx4 v[176:177], off
	s_waitcnt vmcnt(8)
	s_waitcnt lgkmcnt(0)
	s_waitcnt lgkmcnt(0)
	v_mfma_f32_16x16x32_bf16 v[62:65], v[130:133], v[196:199], v[62:65]
	v_mfma_f32_16x16x32_bf16 v[58:61], v[138:141], v[196:199], v[58:61]
	s_barrier
	s_setprio 1
	v_mfma_f32_16x16x32_bf16 v[54:57], v[130:133], v[220:223], v[54:57]
	v_mfma_f32_16x16x32_bf16 v[50:53], v[138:141], v[220:223], v[50:53]
	v_mfma_f32_16x16x32_bf16 v[46:49], v[130:133], v[228:231], v[46:49]
	v_mfma_f32_16x16x32_bf16 v[42:45], v[138:141], v[228:231], v[42:45]
	v_mfma_f32_16x16x32_bf16 v[38:41], v[130:133], v[236:239], v[38:41]
	v_mfma_f32_16x16x32_bf16 v[34:37], v[138:141], v[236:239], v[34:37]
	v_mfma_f32_16x16x32_bf16 v[62:65], v[134:137], v[200:203], v[62:65]
	v_mfma_f32_16x16x32_bf16 v[58:61], v[142:145], v[200:203], v[58:61]
	v_mfma_f32_16x16x32_bf16 v[54:57], v[134:137], v[224:227], v[54:57]
	v_mfma_f32_16x16x32_bf16 v[50:53], v[142:145], v[224:227], v[50:53]
	v_mfma_f32_16x16x32_bf16 v[46:49], v[134:137], v[232:235], v[46:49]
	v_mfma_f32_16x16x32_bf16 v[42:45], v[142:145], v[232:235], v[42:45]
	v_mfma_f32_16x16x32_bf16 v[38:41], v[134:137], v[240:243], v[38:41]
	v_mfma_f32_16x16x32_bf16 v[34:37], v[142:145], v[240:243], v[34:37]
	v_mfma_f32_16x16x32_bf16 v[30:33], v[146:149], v[196:199], v[30:33]
	v_mfma_f32_16x16x32_bf16 v[26:29], v[154:157], v[196:199], v[26:29]
	v_mfma_f32_16x16x32_bf16 v[22:25], v[146:149], v[220:223], v[22:25]
	v_mfma_f32_16x16x32_bf16 v[18:21], v[154:157], v[220:223], v[18:21]
	v_mfma_f32_16x16x32_bf16 v[14:17], v[146:149], v[228:231], v[14:17]
	v_mfma_f32_16x16x32_bf16 v[10:13], v[154:157], v[228:231], v[10:13]
	v_mfma_f32_16x16x32_bf16 v[6:9], v[146:149], v[236:239], v[6:9]
	v_mfma_f32_16x16x32_bf16 v[2:5], v[154:157], v[236:239], v[2:5]
	v_mfma_f32_16x16x32_bf16 v[30:33], v[150:153], v[200:203], v[30:33]
	v_mfma_f32_16x16x32_bf16 v[26:29], v[158:161], v[200:203], v[26:29]
	v_mfma_f32_16x16x32_bf16 v[22:25], v[150:153], v[224:227], v[22:25]
	v_mfma_f32_16x16x32_bf16 v[18:21], v[158:161], v[224:227], v[18:21]
	v_mfma_f32_16x16x32_bf16 v[14:17], v[150:153], v[232:235], v[14:17]
	v_mfma_f32_16x16x32_bf16 v[10:13], v[158:161], v[232:235], v[10:13]
	v_mfma_f32_16x16x32_bf16 v[6:9], v[150:153], v[240:243], v[6:9]
	v_mfma_f32_16x16x32_bf16 v[2:5], v[158:161], v[240:243], v[2:5]
	s_setprio 0
	s_barrier
	s_add_i32 s46, s46, 2
	s_add_u32 s0, s0, 0x100
	s_addc_u32 s1, s1, 0
	s_add_u32 s26, s26, 0x100
	s_addc_u32 s27, s27, 0
	s_cmp_gt_u32 s46, 29
	s_cbranch_scc0 .LBB0_399
	s_and_b64 vcc, exec, s[14:15]
	s_cbranch_vccz .LBB0_402
	s_barrier

.LBB0_846:
	s_add_u32 s3, s0, 0xfff80080
	s_addc_u32 s18, s1, -1
	s_add_i32 s42, 0, 0x10000
	s_cmp_eq_u32 s41, 28
	s_cselect_b32 s21, s13, s18
	s_cselect_b32 s20, s31, s3
	s_cselect_b32 s19, s11, s40
	s_cselect_b32 s18, s34, s35
	s_add_i32 s3, 0, 0x14000
	v_add_u32_e32 v152, s42, v163
	v_add_u32_e32 v160, s3, v163
	ds_read_b128 v[140:143], v152
	ds_read_b128 v[144:147], v152 offset:1024
	ds_read_b128 v[148:151], v152 offset:2048
	ds_read_b128 v[152:155], v152 offset:3072
	ds_read_b128 v[156:159], v160
	ds_read_b128 v[166:169], v160 offset:1024
	ds_read_b128 v[170:173], v160 offset:2048
	ds_read_b128 v[174:177], v160 offset:3072
	v_lshl_add_u64 v[160:161], s[0:1], 0, v[136:137]
	s_add_i32 m0, s22, 0xc000
	ds_read_b128 v[188:191], v165
	ds_read_b128 v[192:195], v165 offset:1024
	ds_read_b128 v[196:199], v165 offset:2048
	ds_read_b128 v[200:203], v165 offset:3072
	ds_read_b128 v[204:207], v165 offset:4096
	ds_read_b128 v[218:221], v165 offset:5120
	ds_read_b128 v[222:225], v165 offset:6144
	ds_read_b128 v[226:229], v165 offset:7168
	global_load_lds_dwordx4 v[160:161], off
	v_lshl_add_u64 v[160:161], s[0:1], 0, v[138:139]
	s_add_i32 m0, s22, 0xe000
	s_nop 0
	global_load_lds_dwordx4 v[160:161], off
	s_waitcnt vmcnt(8)
	s_waitcnt lgkmcnt(0)
	s_waitcnt lgkmcnt(0)
	v_mfma_f32_16x16x32_bf16 v[126:129], v[140:143], v[188:191], v[126:129]
	v_mfma_f32_16x16x32_bf16 v[122:125], v[148:151], v[188:191], v[122:125]
	s_barrier
	s_setprio 1
	v_mfma_f32_16x16x32_bf16 v[110:113], v[140:143], v[196:199], v[110:113]
	v_mfma_f32_16x16x32_bf16 v[106:109], v[148:151], v[196:199], v[106:109]
	v_mfma_f32_16x16x32_bf16 v[94:97], v[140:143], v[204:207], v[94:97]
	v_mfma_f32_16x16x32_bf16 v[90:93], v[148:151], v[204:207], v[90:93]
	v_mfma_f32_16x16x32_bf16 v[78:81], v[140:143], v[222:225], v[78:81]
	v_mfma_f32_16x16x32_bf16 v[74:77], v[148:151], v[222:225], v[74:77]
	v_mfma_f32_16x16x32_bf16 v[126:129], v[144:147], v[192:195], v[126:129]
	v_mfma_f32_16x16x32_bf16 v[122:125], v[152:155], v[192:195], v[122:125]
	v_mfma_f32_16x16x32_bf16 v[110:113], v[144:147], v[200:203], v[110:113]
	v_mfma_f32_16x16x32_bf16 v[106:109], v[152:155], v[200:203], v[106:109]
	v_mfma_f32_16x16x32_bf16 v[94:97], v[144:147], v[218:221], v[94:97]
	v_mfma_f32_16x16x32_bf16 v[90:93], v[152:155], v[218:221], v[90:93]
	v_mfma_f32_16x16x32_bf16 v[78:81], v[144:147], v[226:229], v[78:81]
	v_mfma_f32_16x16x32_bf16 v[74:77], v[152:155], v[226:229], v[74:77]
	v_mfma_f32_16x16x32_bf16 v[118:121], v[156:159], v[188:191], v[118:121]
	v_mfma_f32_16x16x32_bf16 v[114:117], v[170:173], v[188:191], v[114:117]
	v_mfma_f32_16x16x32_bf16 v[102:105], v[156:159], v[196:199], v[102:105]
	v_mfma_f32_16x16x32_bf16 v[98:101], v[170:173], v[196:199], v[98:101]
	v_mfma_f32_16x16x32_bf16 v[86:89], v[156:159], v[204:207], v[86:89]
	v_mfma_f32_16x16x32_bf16 v[82:85], v[170:173], v[204:207], v[82:85]
	v_mfma_f32_16x16x32_bf16 v[70:73], v[156:159], v[222:225], v[70:73]
	v_mfma_f32_16x16x32_bf16 v[66:69], v[170:173], v[222:225], v[66:69]
	v_mfma_f32_16x16x32_bf16 v[118:121], v[166:169], v[192:195], v[118:121]
	v_mfma_f32_16x16x32_bf16 v[114:117], v[174:177], v[192:195], v[114:117]
	v_mfma_f32_16x16x32_bf16 v[102:105], v[166:169], v[200:203], v[102:105]
	v_mfma_f32_16x16x32_bf16 v[98:101], v[174:177], v[200:203], v[98:101]
	v_mfma_f32_16x16x32_bf16 v[86:89], v[166:169], v[218:221], v[86:89]
	v_mfma_f32_16x16x32_bf16 v[82:85], v[174:177], v[218:221], v[82:85]
	v_mfma_f32_16x16x32_bf16 v[70:73], v[166:169], v[226:229], v[70:73]
	v_mfma_f32_16x16x32_bf16 v[66:69], v[174:177], v[226:229], v[66:69]
	s_setprio 0
	s_barrier
	s_add_i32 s42, s42, s2
	v_lshl_add_u64 v[160:161], s[18:19], 0, v[0:1]
	s_mov_b32 m0, s42
	ds_read_b128 v[188:191], v165 offset:16384
	ds_read_b128 v[192:195], v165 offset:17408
	ds_read_b128 v[196:199], v165 offset:18432
	ds_read_b128 v[200:203], v165 offset:19456
	ds_read_b128 v[204:207], v165 offset:20480
	ds_read_b128 v[218:221], v165 offset:21504
	ds_read_b128 v[222:225], v165 offset:22528
	ds_read_b128 v[226:229], v165 offset:23552
	global_load_lds_dwordx4 v[160:161], off
	s_add_i32 m0, s42, 0x2000
	s_add_u32 s44, s18, 0x80000
	v_lshl_add_u64 v[178:179], s[18:19], 0, v[130:131]
	s_addc_u32 s45, s19, 0
	s_add_i32 s3, s3, s2
	global_load_lds_dwordx4 v[178:179], off
	v_lshl_add_u64 v[180:181], s[44:45], 0, v[0:1]
	s_mov_b32 m0, s3
	v_lshl_add_u64 v[182:183], s[20:21], 0, v[132:133]
	global_load_lds_dwordx4 v[180:181], off
	v_lshl_add_u64 v[180:181], s[44:45], 0, v[130:131]
	s_add_i32 m0, s3, 0x2000
	s_nop 0
	global_load_lds_dwordx4 v[180:181], off
	v_lshl_add_u64 v[180:181], s[20:21], 0, v[134:135]
	s_mov_b32 m0, s22
	s_nop 0
	global_load_lds_dwordx4 v[180:181], off
	s_mov_b32 m0, s23
	s_nop 0
	global_load_lds_dwordx4 v[182:183], off
	s_waitcnt vmcnt(8)
	s_waitcnt lgkmcnt(0)
	s_waitcnt lgkmcnt(0)
	v_mfma_f32_16x16x32_bf16 v[62:65], v[140:143], v[188:191], v[62:65]
	v_mfma_f32_16x16x32_bf16 v[58:61], v[148:151], v[188:191], v[58:61]
	s_barrier
	s_setprio 1
	v_mfma_f32_16x16x32_bf16 v[46:49], v[140:143], v[196:199], v[46:49]
	v_mfma_f32_16x16x32_bf16 v[42:45], v[148:151], v[196:199], v[42:45]
	v_mfma_f32_16x16x32_bf16 v[30:33], v[140:143], v[204:207], v[30:33]
	v_mfma_f32_16x16x32_bf16 v[26:29], v[148:151], v[204:207], v[26:29]
	v_mfma_f32_16x16x32_bf16 v[14:17], v[140:143], v[222:225], v[14:17]
	v_mfma_f32_16x16x32_bf16 v[10:13], v[148:151], v[222:225], v[10:13]
	v_mfma_f32_16x16x32_bf16 v[62:65], v[144:147], v[192:195], v[62:65]
	v_mfma_f32_16x16x32_bf16 v[58:61], v[152:155], v[192:195], v[58:61]
	v_mfma_f32_16x16x32_bf16 v[46:49], v[144:147], v[200:203], v[46:49]
	v_mfma_f32_16x16x32_bf16 v[42:45], v[152:155], v[200:203], v[42:45]
	v_mfma_f32_16x16x32_bf16 v[30:33], v[144:147], v[218:221], v[30:33]
	v_mfma_f32_16x16x32_bf16 v[26:29], v[152:155], v[218:221], v[26:29]
	v_mfma_f32_16x16x32_bf16 v[14:17], v[144:147], v[226:229], v[14:17]
	v_mfma_f32_16x16x32_bf16 v[10:13], v[152:155], v[226:229], v[10:13]
	v_mfma_f32_16x16x32_bf16 v[54:57], v[156:159], v[188:191], v[54:57]
	v_mfma_f32_16x16x32_bf16 v[50:53], v[170:173], v[188:191], v[50:53]
	v_mfma_f32_16x16x32_bf16 v[38:41], v[156:159], v[196:199], v[38:41]
	v_mfma_f32_16x16x32_bf16 v[34:37], v[170:173], v[196:199], v[34:37]
	v_mfma_f32_16x16x32_bf16 v[22:25], v[156:159], v[204:207], v[22:25]
	v_mfma_f32_16x16x32_bf16 v[18:21], v[170:173], v[204:207], v[18:21]
	v_mfma_f32_16x16x32_bf16 v[6:9], v[156:159], v[222:225], v[6:9]
	v_mfma_f32_16x16x32_bf16 v[2:5], v[170:173], v[222:225], v[2:5]
	v_mfma_f32_16x16x32_bf16 v[54:57], v[166:169], v[192:195], v[54:57]
	v_mfma_f32_16x16x32_bf16 v[50:53], v[174:177], v[192:195], v[50:53]
	v_mfma_f32_16x16x32_bf16 v[38:41], v[166:169], v[200:203], v[38:41]
	v_mfma_f32_16x16x32_bf16 v[34:37], v[174:177], v[200:203], v[34:37]
	v_mfma_f32_16x16x32_bf16 v[22:25], v[166:169], v[218:221], v[22:25]
	v_mfma_f32_16x16x32_bf16 v[18:21], v[174:177], v[218:221], v[18:21]
	v_mfma_f32_16x16x32_bf16 v[6:9], v[166:169], v[226:229], v[6:9]
	v_mfma_f32_16x16x32_bf16 v[2:5], v[174:177], v[226:229], v[2:5]
	s_setprio 0
	s_barrier
	s_add_i32 s3, 0, 0x18000
	s_add_i32 s42, 0, 0x1c000
	v_add_u32_e32 v152, s3, v163
	v_add_u32_e32 v174, s42, v163
	ds_read_b128 v[140:143], v152
	ds_read_b128 v[144:147], v152 offset:1024
	ds_read_b128 v[148:151], v152 offset:2048
	ds_read_b128 v[152:155], v152 offset:3072
	ds_read_b128 v[156:159], v174
	ds_read_b128 v[166:169], v174 offset:1024
	ds_read_b128 v[170:173], v174 offset:2048
	ds_read_b128 v[174:177], v174 offset:3072
	s_add_u32 s20, s20, 0x80000
	s_addc_u32 s21, s21, 0
	s_mov_b32 m0, s24
	v_lshl_add_u64 v[184:185], s[20:21], 0, v[134:135]
	ds_read_b128 v[188:191], v165 offset:32768
	ds_read_b128 v[192:195], v165 offset:33792
	ds_read_b128 v[196:199], v165 offset:34816
	ds_read_b128 v[200:203], v165 offset:35840
	ds_read_b128 v[204:207], v165 offset:36864
	ds_read_b128 v[218:221], v165 offset:37888
	ds_read_b128 v[222:225], v165 offset:38912
	ds_read_b128 v[226:229], v165 offset:39936
	global_load_lds_dwordx4 v[184:185], off
	v_lshl_add_u64 v[184:185], s[20:21], 0, v[132:133]
	s_mov_b32 m0, s25
	s_nop 0
	global_load_lds_dwordx4 v[184:185], off
	s_waitcnt vmcnt(8)
	s_waitcnt lgkmcnt(0)
	s_waitcnt lgkmcnt(0)
	v_mfma_f32_16x16x32_bf16 v[126:129], v[140:143], v[188:191], v[126:129]
	v_mfma_f32_16x16x32_bf16 v[122:125], v[148:151], v[188:191], v[122:125]
	s_barrier
	s_setprio 1
	v_mfma_f32_16x16x32_bf16 v[110:113], v[140:143], v[196:199], v[110:113]
	v_mfma_f32_16x16x32_bf16 v[106:109], v[148:151], v[196:199], v[106:109]
	v_mfma_f32_16x16x32_bf16 v[94:97], v[140:143], v[204:207], v[94:97]
	v_mfma_f32_16x16x32_bf16 v[90:93], v[148:151], v[204:207], v[90:93]
	v_mfma_f32_16x16x32_bf16 v[78:81], v[140:143], v[222:225], v[78:81]
	v_mfma_f32_16x16x32_bf16 v[74:77], v[148:151], v[222:225], v[74:77]
	v_mfma_f32_16x16x32_bf16 v[126:129], v[144:147], v[192:195], v[126:129]
	v_mfma_f32_16x16x32_bf16 v[122:125], v[152:155], v[192:195], v[122:125]
	v_mfma_f32_16x16x32_bf16 v[110:113], v[144:147], v[200:203], v[110:113]
	v_mfma_f32_16x16x32_bf16 v[106:109], v[152:155], v[200:203], v[106:109]
	v_mfma_f32_16x16x32_bf16 v[94:97], v[144:147], v[218:221], v[94:97]
	v_mfma_f32_16x16x32_bf16 v[90:93], v[152:155], v[218:221], v[90:93]
	v_mfma_f32_16x16x32_bf16 v[78:81], v[144:147], v[226:229], v[78:81]
	v_mfma_f32_16x16x32_bf16 v[74:77], v[152:155], v[226:229], v[74:77]
	v_mfma_f32_16x16x32_bf16 v[118:121], v[156:159], v[188:191], v[118:121]
	v_mfma_f32_16x16x32_bf16 v[114:117], v[170:173], v[188:191], v[114:117]
	v_mfma_f32_16x16x32_bf16 v[102:105], v[156:159], v[196:199], v[102:105]
	v_mfma_f32_16x16x32_bf16 v[98:101], v[170:173], v[196:199], v[98:101]
	v_mfma_f32_16x16x32_bf16 v[86:89], v[156:159], v[204:207], v[86:89]
	v_mfma_f32_16x16x32_bf16 v[82:85], v[170:173], v[204:207], v[82:85]
	v_mfma_f32_16x16x32_bf16 v[70:73], v[156:159], v[222:225], v[70:73]
	v_mfma_f32_16x16x32_bf16 v[66:69], v[170:173], v[222:225], v[66:69]
	v_mfma_f32_16x16x32_bf16 v[118:121], v[166:169], v[192:195], v[118:121]
	v_mfma_f32_16x16x32_bf16 v[114:117], v[174:177], v[192:195], v[114:117]
	v_mfma_f32_16x16x32_bf16 v[102:105], v[166:169], v[200:203], v[102:105]
	v_mfma_f32_16x16x32_bf16 v[98:101], v[174:177], v[200:203], v[98:101]
	v_mfma_f32_16x16x32_bf16 v[86:89], v[166:169], v[218:221], v[86:89]
	v_mfma_f32_16x16x32_bf16 v[82:85], v[174:177], v[218:221], v[82:85]
	v_mfma_f32_16x16x32_bf16 v[70:73], v[166:169], v[226:229], v[70:73]
	v_mfma_f32_16x16x32_bf16 v[66:69], v[174:177], v[226:229], v[66:69]
	s_setprio 0
	s_barrier
	s_add_i32 s3, s3, s2
	v_lshl_add_u64 v[160:161], v[160:161], 0, s[52:53]
	s_mov_b32 m0, s3
	ds_read_b128 v[188:191], v165 offset:49152
	ds_read_b128 v[192:195], v165 offset:50176
	ds_read_b128 v[196:199], v165 offset:51200
	ds_read_b128 v[200:203], v165 offset:52224
	ds_read_b128 v[204:207], v165 offset:53248
	ds_read_b128 v[218:221], v165 offset:54272
	ds_read_b128 v[222:225], v165 offset:55296
	ds_read_b128 v[226:229], v165 offset:56320
	global_load_lds_dwordx4 v[160:161], off
	s_add_i32 m0, s3, 0x2000
	s_add_u32 s18, s18, 0x80080
	v_lshl_add_u64 v[160:161], v[178:179], 0, s[52:53]
	s_addc_u32 s19, s19, 0
	s_add_i32 s3, s42, s2
	global_load_lds_dwordx4 v[160:161], off
	v_lshl_add_u64 v[160:161], s[18:19], 0, v[0:1]
	s_mov_b32 m0, s3
	s_nop 0
	global_load_lds_dwordx4 v[160:161], off
	v_lshl_add_u64 v[160:161], s[18:19], 0, v[130:131]
	s_add_i32 m0, s3, 0x2000
	s_nop 0
	global_load_lds_dwordx4 v[160:161], off
	v_lshl_add_u64 v[160:161], v[180:181], 0, s[52:53]
	s_mov_b32 m0, s26
	s_nop 0
	global_load_lds_dwordx4 v[160:161], off
	v_lshl_add_u64 v[160:161], v[182:183], 0, s[52:53]
	s_mov_b32 m0, s27
	s_nop 0
	global_load_lds_dwordx4 v[160:161], off
	s_waitcnt vmcnt(8)
	s_waitcnt lgkmcnt(0)
	s_waitcnt lgkmcnt(0)
	v_mfma_f32_16x16x32_bf16 v[62:65], v[140:143], v[188:191], v[62:65]
	v_mfma_f32_16x16x32_bf16 v[58:61], v[148:151], v[188:191], v[58:61]
	s_barrier
	s_setprio 1
	v_mfma_f32_16x16x32_bf16 v[46:49], v[140:143], v[196:199], v[46:49]
	v_mfma_f32_16x16x32_bf16 v[42:45], v[148:151], v[196:199], v[42:45]
	v_mfma_f32_16x16x32_bf16 v[30:33], v[140:143], v[204:207], v[30:33]
	v_mfma_f32_16x16x32_bf16 v[26:29], v[148:151], v[204:207], v[26:29]
	v_mfma_f32_16x16x32_bf16 v[14:17], v[140:143], v[222:225], v[14:17]
	v_mfma_f32_16x16x32_bf16 v[10:13], v[148:151], v[222:225], v[10:13]
	v_mfma_f32_16x16x32_bf16 v[62:65], v[144:147], v[192:195], v[62:65]
	v_mfma_f32_16x16x32_bf16 v[58:61], v[152:155], v[192:195], v[58:61]
	v_mfma_f32_16x16x32_bf16 v[46:49], v[144:147], v[200:203], v[46:49]
	v_mfma_f32_16x16x32_bf16 v[42:45], v[152:155], v[200:203], v[42:45]
	v_mfma_f32_16x16x32_bf16 v[30:33], v[144:147], v[218:221], v[30:33]
	v_mfma_f32_16x16x32_bf16 v[26:29], v[152:155], v[218:221], v[26:29]
	v_mfma_f32_16x16x32_bf16 v[14:17], v[144:147], v[226:229], v[14:17]
	v_mfma_f32_16x16x32_bf16 v[10:13], v[152:155], v[226:229], v[10:13]
	v_mfma_f32_16x16x32_bf16 v[54:57], v[156:159], v[188:191], v[54:57]
	v_mfma_f32_16x16x32_bf16 v[50:53], v[170:173], v[188:191], v[50:53]
	v_mfma_f32_16x16x32_bf16 v[38:41], v[156:159], v[196:199], v[38:41]
	v_mfma_f32_16x16x32_bf16 v[34:37], v[170:173], v[196:199], v[34:37]
	v_mfma_f32_16x16x32_bf16 v[22:25], v[156:159], v[204:207], v[22:25]
	v_mfma_f32_16x16x32_bf16 v[18:21], v[170:173], v[204:207], v[18:21]
	v_mfma_f32_16x16x32_bf16 v[6:9], v[156:159], v[222:225], v[6:9]
	v_mfma_f32_16x16x32_bf16 v[2:5], v[170:173], v[222:225], v[2:5]
	v_mfma_f32_16x16x32_bf16 v[54:57], v[166:169], v[192:195], v[54:57]
	v_mfma_f32_16x16x32_bf16 v[50:53], v[174:177], v[192:195], v[50:53]
	v_mfma_f32_16x16x32_bf16 v[38:41], v[166:169], v[200:203], v[38:41]
	v_mfma_f32_16x16x32_bf16 v[34:37], v[174:177], v[200:203], v[34:37]
	v_mfma_f32_16x16x32_bf16 v[22:25], v[166:169], v[218:221], v[22:25]
	v_mfma_f32_16x16x32_bf16 v[18:21], v[174:177], v[218:221], v[18:21]
	v_mfma_f32_16x16x32_bf16 v[6:9], v[166:169], v[226:229], v[6:9]
	v_mfma_f32_16x16x32_bf16 v[2:5], v[174:177], v[226:229], v[2:5]
	s_setprio 0
	s_barrier
	s_add_i32 s41, s41, 2
	s_add_u32 s0, s0, 0x100
	s_addc_u32 s1, s1, 0
	s_add_u32 s35, s35, 0x100
	s_addc_u32 s40, s40, 0
	s_cmp_gt_u32 s41, 29
	s_cbranch_scc0 .LBB0_846
	s_and_b64 vcc, exec, s[8:9]
	s_movk_i32 s40, 0x4000
	s_movk_i32 s41, 0x6000
	s_cbranch_vccz .LBB0_849
	s_barrier

.LBB0_959:
	s_add_u32 s3, s16, 0xfff80080
	s_addc_u32 s18, s17, -1
	s_add_i32 s42, 0, 0x10000
	s_cmp_eq_u32 s46, 28
	s_cselect_b32 s21, s11, s18
	s_cselect_b32 s20, s40, s3
	v_add_u32_e32 v140, s42, v143
	s_cselect_b32 s19, s9, s45
	s_cselect_b32 s18, s41, s44
	s_add_i32 s3, 0, 0x14000
	ds_read_b128 v[146:149], v140
	ds_read_b128 v[150:153], v140 offset:1024
	ds_read_b128 v[154:157], v140 offset:2048
	ds_read_b128 v[158:161], v140 offset:3072
	v_add_u32_e32 v140, s3, v143
	ds_read_b128 v[162:165], v140
	ds_read_b128 v[166:169], v140 offset:1024
	ds_read_b128 v[170:173], v140 offset:2048
	ds_read_b128 v[174:177], v140 offset:3072
	v_lshl_add_u64 v[140:141], s[16:17], 0, v[136:137]
	s_add_i32 m0, s25, 0xc000
	ds_read_b128 v[188:191], v145
	ds_read_b128 v[192:195], v145 offset:1024
	ds_read_b128 v[196:199], v145 offset:2048
	ds_read_b128 v[200:203], v145 offset:3072
	ds_read_b128 v[204:207], v145 offset:4096
	ds_read_b128 v[218:221], v145 offset:5120
	ds_read_b128 v[222:225], v145 offset:6144
	ds_read_b128 v[226:229], v145 offset:7168
	global_load_lds_dwordx4 v[140:141], off
	v_lshl_add_u64 v[140:141], s[16:17], 0, v[138:139]
	s_add_i32 m0, s25, 0xe000
	s_nop 0
	global_load_lds_dwordx4 v[140:141], off
	s_waitcnt vmcnt(8)
	s_waitcnt lgkmcnt(0)
	s_waitcnt lgkmcnt(0)
	v_mfma_f32_16x16x32_bf16 v[126:129], v[146:149], v[188:191], v[126:129]
	v_mfma_f32_16x16x32_bf16 v[122:125], v[154:157], v[188:191], v[122:125]
	s_barrier
	s_setprio 1
	v_mfma_f32_16x16x32_bf16 v[110:113], v[146:149], v[196:199], v[110:113]
	v_mfma_f32_16x16x32_bf16 v[106:109], v[154:157], v[196:199], v[106:109]
	v_mfma_f32_16x16x32_bf16 v[94:97], v[146:149], v[204:207], v[94:97]
	v_mfma_f32_16x16x32_bf16 v[90:93], v[154:157], v[204:207], v[90:93]
	v_mfma_f32_16x16x32_bf16 v[78:81], v[146:149], v[222:225], v[78:81]
	v_mfma_f32_16x16x32_bf16 v[74:77], v[154:157], v[222:225], v[74:77]
	v_mfma_f32_16x16x32_bf16 v[126:129], v[150:153], v[192:195], v[126:129]
	v_mfma_f32_16x16x32_bf16 v[122:125], v[158:161], v[192:195], v[122:125]
	v_mfma_f32_16x16x32_bf16 v[110:113], v[150:153], v[200:203], v[110:113]
	v_mfma_f32_16x16x32_bf16 v[106:109], v[158:161], v[200:203], v[106:109]
	v_mfma_f32_16x16x32_bf16 v[94:97], v[150:153], v[218:221], v[94:97]
	v_mfma_f32_16x16x32_bf16 v[90:93], v[158:161], v[218:221], v[90:93]
	v_mfma_f32_16x16x32_bf16 v[78:81], v[150:153], v[226:229], v[78:81]
	v_mfma_f32_16x16x32_bf16 v[74:77], v[158:161], v[226:229], v[74:77]
	v_mfma_f32_16x16x32_bf16 v[118:121], v[162:165], v[188:191], v[118:121]
	v_mfma_f32_16x16x32_bf16 v[114:117], v[170:173], v[188:191], v[114:117]
	v_mfma_f32_16x16x32_bf16 v[102:105], v[162:165], v[196:199], v[102:105]
	v_mfma_f32_16x16x32_bf16 v[98:101], v[170:173], v[196:199], v[98:101]
	v_mfma_f32_16x16x32_bf16 v[86:89], v[162:165], v[204:207], v[86:89]
	v_mfma_f32_16x16x32_bf16 v[82:85], v[170:173], v[204:207], v[82:85]
	v_mfma_f32_16x16x32_bf16 v[70:73], v[162:165], v[222:225], v[70:73]
	v_mfma_f32_16x16x32_bf16 v[66:69], v[170:173], v[222:225], v[66:69]
	v_mfma_f32_16x16x32_bf16 v[118:121], v[166:169], v[192:195], v[118:121]
	v_mfma_f32_16x16x32_bf16 v[114:117], v[174:177], v[192:195], v[114:117]
	v_mfma_f32_16x16x32_bf16 v[102:105], v[166:169], v[200:203], v[102:105]
	v_mfma_f32_16x16x32_bf16 v[98:101], v[174:177], v[200:203], v[98:101]
	v_mfma_f32_16x16x32_bf16 v[86:89], v[166:169], v[218:221], v[86:89]
	v_mfma_f32_16x16x32_bf16 v[82:85], v[174:177], v[218:221], v[82:85]
	v_mfma_f32_16x16x32_bf16 v[70:73], v[166:169], v[226:229], v[70:73]
	v_mfma_f32_16x16x32_bf16 v[66:69], v[174:177], v[226:229], v[66:69]
	s_setprio 0
	s_barrier
	s_add_i32 s42, s42, s24
	v_lshl_add_u64 v[140:141], s[18:19], 0, v[0:1]
	s_mov_b32 m0, s42
	ds_read_b128 v[188:191], v145 offset:16384
	ds_read_b128 v[192:195], v145 offset:17408
	ds_read_b128 v[196:199], v145 offset:18432
	ds_read_b128 v[200:203], v145 offset:19456
	ds_read_b128 v[204:207], v145 offset:20480
	ds_read_b128 v[218:221], v145 offset:21504
	ds_read_b128 v[222:225], v145 offset:22528
	ds_read_b128 v[226:229], v145 offset:23552
	global_load_lds_dwordx4 v[140:141], off
	s_add_i32 m0, s42, 0x2000
	s_add_u32 s56, s18, 0x80000
	v_lshl_add_u64 v[178:179], s[18:19], 0, v[130:131]
	s_addc_u32 s57, s19, 0
	s_add_i32 s3, s3, s24
	global_load_lds_dwordx4 v[178:179], off
	v_lshl_add_u64 v[180:181], s[56:57], 0, v[0:1]
	s_mov_b32 m0, s3
	v_lshl_add_u64 v[182:183], s[20:21], 0, v[132:133]
	global_load_lds_dwordx4 v[180:181], off
	v_lshl_add_u64 v[180:181], s[56:57], 0, v[130:131]
	s_add_i32 m0, s3, 0x2000
	s_nop 0
	global_load_lds_dwordx4 v[180:181], off
	v_lshl_add_u64 v[180:181], s[20:21], 0, v[134:135]
	s_mov_b32 m0, s25
	s_nop 0
	global_load_lds_dwordx4 v[180:181], off
	s_mov_b32 m0, s26
	s_nop 0
	global_load_lds_dwordx4 v[182:183], off
	s_waitcnt vmcnt(8)
	s_waitcnt lgkmcnt(0)
	s_waitcnt lgkmcnt(0)
	v_mfma_f32_16x16x32_bf16 v[62:65], v[146:149], v[188:191], v[62:65]
	v_mfma_f32_16x16x32_bf16 v[58:61], v[154:157], v[188:191], v[58:61]
	s_barrier
	s_setprio 1
	v_mfma_f32_16x16x32_bf16 v[46:49], v[146:149], v[196:199], v[46:49]
	v_mfma_f32_16x16x32_bf16 v[42:45], v[154:157], v[196:199], v[42:45]
	v_mfma_f32_16x16x32_bf16 v[30:33], v[146:149], v[204:207], v[30:33]
	v_mfma_f32_16x16x32_bf16 v[26:29], v[154:157], v[204:207], v[26:29]
	v_mfma_f32_16x16x32_bf16 v[14:17], v[146:149], v[222:225], v[14:17]
	v_mfma_f32_16x16x32_bf16 v[10:13], v[154:157], v[222:225], v[10:13]
	v_mfma_f32_16x16x32_bf16 v[62:65], v[150:153], v[192:195], v[62:65]
	v_mfma_f32_16x16x32_bf16 v[58:61], v[158:161], v[192:195], v[58:61]
	v_mfma_f32_16x16x32_bf16 v[46:49], v[150:153], v[200:203], v[46:49]
	v_mfma_f32_16x16x32_bf16 v[42:45], v[158:161], v[200:203], v[42:45]
	v_mfma_f32_16x16x32_bf16 v[30:33], v[150:153], v[218:221], v[30:33]
	v_mfma_f32_16x16x32_bf16 v[26:29], v[158:161], v[218:221], v[26:29]
	v_mfma_f32_16x16x32_bf16 v[14:17], v[150:153], v[226:229], v[14:17]
	v_mfma_f32_16x16x32_bf16 v[10:13], v[158:161], v[226:229], v[10:13]
	v_mfma_f32_16x16x32_bf16 v[54:57], v[162:165], v[188:191], v[54:57]
	v_mfma_f32_16x16x32_bf16 v[50:53], v[170:173], v[188:191], v[50:53]
	v_mfma_f32_16x16x32_bf16 v[38:41], v[162:165], v[196:199], v[38:41]
	v_mfma_f32_16x16x32_bf16 v[34:37], v[170:173], v[196:199], v[34:37]
	v_mfma_f32_16x16x32_bf16 v[22:25], v[162:165], v[204:207], v[22:25]
	v_mfma_f32_16x16x32_bf16 v[18:21], v[170:173], v[204:207], v[18:21]
	v_mfma_f32_16x16x32_bf16 v[6:9], v[162:165], v[222:225], v[6:9]
	v_mfma_f32_16x16x32_bf16 v[2:5], v[170:173], v[222:225], v[2:5]
	v_mfma_f32_16x16x32_bf16 v[54:57], v[166:169], v[192:195], v[54:57]
	v_mfma_f32_16x16x32_bf16 v[50:53], v[174:177], v[192:195], v[50:53]
	v_mfma_f32_16x16x32_bf16 v[38:41], v[166:169], v[200:203], v[38:41]
	v_mfma_f32_16x16x32_bf16 v[34:37], v[174:177], v[200:203], v[34:37]
	v_mfma_f32_16x16x32_bf16 v[22:25], v[166:169], v[218:221], v[22:25]
	v_mfma_f32_16x16x32_bf16 v[18:21], v[174:177], v[218:221], v[18:21]
	v_mfma_f32_16x16x32_bf16 v[6:9], v[166:169], v[226:229], v[6:9]
	v_mfma_f32_16x16x32_bf16 v[2:5], v[174:177], v[226:229], v[2:5]
	s_setprio 0
	s_barrier
	s_add_i32 s3, 0, 0x18000
	s_add_i32 s42, 0, 0x1c000
	v_add_u32_e32 v158, s3, v143
	v_add_u32_e32 v174, s42, v143
	ds_read_b128 v[146:149], v158
	ds_read_b128 v[150:153], v158 offset:1024
	ds_read_b128 v[154:157], v158 offset:2048
	ds_read_b128 v[158:161], v158 offset:3072
	ds_read_b128 v[162:165], v174
	ds_read_b128 v[166:169], v174 offset:1024
	ds_read_b128 v[170:173], v174 offset:2048
	ds_read_b128 v[174:177], v174 offset:3072
	s_add_u32 s20, s20, 0x80000
	s_addc_u32 s21, s21, 0
	s_mov_b32 m0, s27
	v_lshl_add_u64 v[184:185], s[20:21], 0, v[134:135]
	ds_read_b128 v[188:191], v145 offset:32768
	ds_read_b128 v[192:195], v145 offset:33792
	ds_read_b128 v[196:199], v145 offset:34816
	ds_read_b128 v[200:203], v145 offset:35840
	ds_read_b128 v[204:207], v145 offset:36864
	ds_read_b128 v[218:221], v145 offset:37888
	ds_read_b128 v[222:225], v145 offset:38912
	ds_read_b128 v[226:229], v145 offset:39936
	global_load_lds_dwordx4 v[184:185], off
	v_lshl_add_u64 v[184:185], s[20:21], 0, v[132:133]
	s_mov_b32 m0, s28
	s_nop 0
	global_load_lds_dwordx4 v[184:185], off
	s_waitcnt vmcnt(8)
	s_waitcnt lgkmcnt(0)
	s_waitcnt lgkmcnt(0)
	v_mfma_f32_16x16x32_bf16 v[126:129], v[146:149], v[188:191], v[126:129]
	v_mfma_f32_16x16x32_bf16 v[122:125], v[154:157], v[188:191], v[122:125]
	s_barrier
	s_setprio 1
	v_mfma_f32_16x16x32_bf16 v[110:113], v[146:149], v[196:199], v[110:113]
	v_mfma_f32_16x16x32_bf16 v[106:109], v[154:157], v[196:199], v[106:109]
	v_mfma_f32_16x16x32_bf16 v[94:97], v[146:149], v[204:207], v[94:97]
	v_mfma_f32_16x16x32_bf16 v[90:93], v[154:157], v[204:207], v[90:93]
	v_mfma_f32_16x16x32_bf16 v[78:81], v[146:149], v[222:225], v[78:81]
	v_mfma_f32_16x16x32_bf16 v[74:77], v[154:157], v[222:225], v[74:77]
	v_mfma_f32_16x16x32_bf16 v[126:129], v[150:153], v[192:195], v[126:129]
	v_mfma_f32_16x16x32_bf16 v[122:125], v[158:161], v[192:195], v[122:125]
	v_mfma_f32_16x16x32_bf16 v[110:113], v[150:153], v[200:203], v[110:113]
	v_mfma_f32_16x16x32_bf16 v[106:109], v[158:161], v[200:203], v[106:109]
	v_mfma_f32_16x16x32_bf16 v[94:97], v[150:153], v[218:221], v[94:97]
	v_mfma_f32_16x16x32_bf16 v[90:93], v[158:161], v[218:221], v[90:93]
	v_mfma_f32_16x16x32_bf16 v[78:81], v[150:153], v[226:229], v[78:81]
	v_mfma_f32_16x16x32_bf16 v[74:77], v[158:161], v[226:229], v[74:77]
	v_mfma_f32_16x16x32_bf16 v[118:121], v[162:165], v[188:191], v[118:121]
	v_mfma_f32_16x16x32_bf16 v[114:117], v[170:173], v[188:191], v[114:117]
	v_mfma_f32_16x16x32_bf16 v[102:105], v[162:165], v[196:199], v[102:105]
	v_mfma_f32_16x16x32_bf16 v[98:101], v[170:173], v[196:199], v[98:101]
	v_mfma_f32_16x16x32_bf16 v[86:89], v[162:165], v[204:207], v[86:89]
	v_mfma_f32_16x16x32_bf16 v[82:85], v[170:173], v[204:207], v[82:85]
	v_mfma_f32_16x16x32_bf16 v[70:73], v[162:165], v[222:225], v[70:73]
	v_mfma_f32_16x16x32_bf16 v[66:69], v[170:173], v[222:225], v[66:69]
	v_mfma_f32_16x16x32_bf16 v[118:121], v[166:169], v[192:195], v[118:121]
	v_mfma_f32_16x16x32_bf16 v[114:117], v[174:177], v[192:195], v[114:117]
	v_mfma_f32_16x16x32_bf16 v[102:105], v[166:169], v[200:203], v[102:105]
	v_mfma_f32_16x16x32_bf16 v[98:101], v[174:177], v[200:203], v[98:101]
	v_mfma_f32_16x16x32_bf16 v[86:89], v[166:169], v[218:221], v[86:89]
	v_mfma_f32_16x16x32_bf16 v[82:85], v[174:177], v[218:221], v[82:85]
	v_mfma_f32_16x16x32_bf16 v[70:73], v[166:169], v[226:229], v[70:73]
	v_mfma_f32_16x16x32_bf16 v[66:69], v[174:177], v[226:229], v[66:69]
	s_setprio 0
	s_barrier
	s_add_i32 s3, s3, s24
	v_lshl_add_u64 v[140:141], v[140:141], 0, s[52:53]
	s_mov_b32 m0, s3
	ds_read_b128 v[188:191], v145 offset:49152
	ds_read_b128 v[192:195], v145 offset:50176
	ds_read_b128 v[196:199], v145 offset:51200
	ds_read_b128 v[200:203], v145 offset:52224
	ds_read_b128 v[204:207], v145 offset:53248
	ds_read_b128 v[218:221], v145 offset:54272
	ds_read_b128 v[222:225], v145 offset:55296
	ds_read_b128 v[226:229], v145 offset:56320
	global_load_lds_dwordx4 v[140:141], off
	s_add_i32 m0, s3, 0x2000
	s_add_u32 s18, s18, 0x80080
	v_lshl_add_u64 v[140:141], v[178:179], 0, s[52:53]
	s_addc_u32 s19, s19, 0
	s_add_i32 s3, s42, s24
	global_load_lds_dwordx4 v[140:141], off
	v_lshl_add_u64 v[140:141], s[18:19], 0, v[0:1]
	s_mov_b32 m0, s3
	s_nop 0
	global_load_lds_dwordx4 v[140:141], off
	v_lshl_add_u64 v[140:141], s[18:19], 0, v[130:131]
	s_add_i32 m0, s3, 0x2000
	s_nop 0
	global_load_lds_dwordx4 v[140:141], off
	v_lshl_add_u64 v[140:141], v[180:181], 0, s[52:53]
	s_mov_b32 m0, s29
	s_nop 0
	global_load_lds_dwordx4 v[140:141], off
	v_lshl_add_u64 v[140:141], v[182:183], 0, s[52:53]
	s_mov_b32 m0, s30
	s_nop 0
	global_load_lds_dwordx4 v[140:141], off
	s_waitcnt vmcnt(8)
	s_waitcnt lgkmcnt(0)
	s_waitcnt lgkmcnt(0)
	v_mfma_f32_16x16x32_bf16 v[62:65], v[146:149], v[188:191], v[62:65]
	v_mfma_f32_16x16x32_bf16 v[58:61], v[154:157], v[188:191], v[58:61]
	s_barrier
	s_setprio 1
	v_mfma_f32_16x16x32_bf16 v[46:49], v[146:149], v[196:199], v[46:49]
	v_mfma_f32_16x16x32_bf16 v[42:45], v[154:157], v[196:199], v[42:45]
	v_mfma_f32_16x16x32_bf16 v[30:33], v[146:149], v[204:207], v[30:33]
	v_mfma_f32_16x16x32_bf16 v[26:29], v[154:157], v[204:207], v[26:29]
	v_mfma_f32_16x16x32_bf16 v[14:17], v[146:149], v[222:225], v[14:17]
	v_mfma_f32_16x16x32_bf16 v[10:13], v[154:157], v[222:225], v[10:13]
	v_mfma_f32_16x16x32_bf16 v[62:65], v[150:153], v[192:195], v[62:65]
	v_mfma_f32_16x16x32_bf16 v[58:61], v[158:161], v[192:195], v[58:61]
	v_mfma_f32_16x16x32_bf16 v[46:49], v[150:153], v[200:203], v[46:49]
	v_mfma_f32_16x16x32_bf16 v[42:45], v[158:161], v[200:203], v[42:45]
	v_mfma_f32_16x16x32_bf16 v[30:33], v[150:153], v[218:221], v[30:33]
	v_mfma_f32_16x16x32_bf16 v[26:29], v[158:161], v[218:221], v[26:29]
	v_mfma_f32_16x16x32_bf16 v[14:17], v[150:153], v[226:229], v[14:17]
	v_mfma_f32_16x16x32_bf16 v[10:13], v[158:161], v[226:229], v[10:13]
	v_mfma_f32_16x16x32_bf16 v[54:57], v[162:165], v[188:191], v[54:57]
	v_mfma_f32_16x16x32_bf16 v[50:53], v[170:173], v[188:191], v[50:53]
	v_mfma_f32_16x16x32_bf16 v[38:41], v[162:165], v[196:199], v[38:41]
	v_mfma_f32_16x16x32_bf16 v[34:37], v[170:173], v[196:199], v[34:37]
	v_mfma_f32_16x16x32_bf16 v[22:25], v[162:165], v[204:207], v[22:25]
	v_mfma_f32_16x16x32_bf16 v[18:21], v[170:173], v[204:207], v[18:21]
	v_mfma_f32_16x16x32_bf16 v[6:9], v[162:165], v[222:225], v[6:9]
	v_mfma_f32_16x16x32_bf16 v[2:5], v[170:173], v[222:225], v[2:5]
	v_mfma_f32_16x16x32_bf16 v[54:57], v[166:169], v[192:195], v[54:57]
	v_mfma_f32_16x16x32_bf16 v[50:53], v[174:177], v[192:195], v[50:53]
	v_mfma_f32_16x16x32_bf16 v[38:41], v[166:169], v[200:203], v[38:41]
	v_mfma_f32_16x16x32_bf16 v[34:37], v[174:177], v[200:203], v[34:37]
	v_mfma_f32_16x16x32_bf16 v[22:25], v[166:169], v[218:221], v[22:25]
	v_mfma_f32_16x16x32_bf16 v[18:21], v[174:177], v[218:221], v[18:21]
	v_mfma_f32_16x16x32_bf16 v[6:9], v[166:169], v[226:229], v[6:9]
	v_mfma_f32_16x16x32_bf16 v[2:5], v[174:177], v[226:229], v[2:5]
	s_setprio 0
	s_barrier
	s_add_i32 s46, s46, 2
	s_add_u32 s16, s16, 0x100
	s_addc_u32 s17, s17, 0
	s_add_u32 s44, s44, 0x100
	s_addc_u32 s45, s45, 0
	s_cmp_gt_u32 s46, 29
	s_cbranch_scc0 .LBB0_959
	s_and_b64 vcc, exec, s[6:7]
	s_movk_i32 s40, 0x4000
	s_movk_i32 s41, 0x6000
	s_mov_b32 s44, 0x8000
	s_mov_b32 s45, 0xa000
	s_cbranch_vccz .LBB0_962
	s_barrier

.LBB0_1024:
	s_add_u32 s3, s20, 0xffe00080
	s_addc_u32 s22, s21, -1
	s_add_i32 s42, 0, 0x10000
	s_cmpk_eq_i32 s57, 0x7c
	s_cselect_b32 s25, s15, s22
	s_cselect_b32 s24, s45, s3
	s_cselect_b32 s23, s13, s56
	s_cselect_b32 s22, s46, s47
	s_add_i32 s3, 0, 0x14000
	v_add_u32_e32 v152, s42, v163
	v_add_u32_e32 v160, s3, v163
	ds_read_b128 v[140:143], v152
	ds_read_b128 v[144:147], v152 offset:1024
	ds_read_b128 v[148:151], v152 offset:2048
	ds_read_b128 v[152:155], v152 offset:3072
	ds_read_b128 v[156:159], v160
	ds_read_b128 v[166:169], v160 offset:1024
	ds_read_b128 v[170:173], v160 offset:2048
	ds_read_b128 v[174:177], v160 offset:3072
	v_lshl_add_u64 v[160:161], s[20:21], 0, v[136:137]
	s_add_i32 m0, s28, 0xc000
	ds_read_b128 v[188:191], v165
	ds_read_b128 v[192:195], v165 offset:1024
	ds_read_b128 v[196:199], v165 offset:2048
	ds_read_b128 v[200:203], v165 offset:3072
	ds_read_b128 v[204:207], v165 offset:4096
	ds_read_b128 v[218:221], v165 offset:5120
	ds_read_b128 v[222:225], v165 offset:6144
	ds_read_b128 v[226:229], v165 offset:7168
	global_load_lds_dwordx4 v[160:161], off
	v_lshl_add_u64 v[160:161], s[20:21], 0, v[138:139]
	s_add_i32 m0, s28, 0xe000
	s_nop 0
	global_load_lds_dwordx4 v[160:161], off
	s_waitcnt vmcnt(8)
	s_waitcnt lgkmcnt(0)
	s_waitcnt lgkmcnt(0)
	v_mfma_f32_16x16x32_bf16 v[126:129], v[140:143], v[188:191], v[126:129]
	v_mfma_f32_16x16x32_bf16 v[122:125], v[148:151], v[188:191], v[122:125]
	s_barrier
	s_setprio 1
	v_mfma_f32_16x16x32_bf16 v[110:113], v[140:143], v[196:199], v[110:113]
	v_mfma_f32_16x16x32_bf16 v[106:109], v[148:151], v[196:199], v[106:109]
	v_mfma_f32_16x16x32_bf16 v[94:97], v[140:143], v[204:207], v[94:97]
	v_mfma_f32_16x16x32_bf16 v[90:93], v[148:151], v[204:207], v[90:93]
	v_mfma_f32_16x16x32_bf16 v[78:81], v[140:143], v[222:225], v[78:81]
	v_mfma_f32_16x16x32_bf16 v[74:77], v[148:151], v[222:225], v[74:77]
	v_mfma_f32_16x16x32_bf16 v[126:129], v[144:147], v[192:195], v[126:129]
	v_mfma_f32_16x16x32_bf16 v[122:125], v[152:155], v[192:195], v[122:125]
	v_mfma_f32_16x16x32_bf16 v[110:113], v[144:147], v[200:203], v[110:113]
	v_mfma_f32_16x16x32_bf16 v[106:109], v[152:155], v[200:203], v[106:109]
	v_mfma_f32_16x16x32_bf16 v[94:97], v[144:147], v[218:221], v[94:97]
	v_mfma_f32_16x16x32_bf16 v[90:93], v[152:155], v[218:221], v[90:93]
	v_mfma_f32_16x16x32_bf16 v[78:81], v[144:147], v[226:229], v[78:81]
	v_mfma_f32_16x16x32_bf16 v[74:77], v[152:155], v[226:229], v[74:77]
	v_mfma_f32_16x16x32_bf16 v[118:121], v[156:159], v[188:191], v[118:121]
	v_mfma_f32_16x16x32_bf16 v[114:117], v[170:173], v[188:191], v[114:117]
	v_mfma_f32_16x16x32_bf16 v[102:105], v[156:159], v[196:199], v[102:105]
	v_mfma_f32_16x16x32_bf16 v[98:101], v[170:173], v[196:199], v[98:101]
	v_mfma_f32_16x16x32_bf16 v[86:89], v[156:159], v[204:207], v[86:89]
	v_mfma_f32_16x16x32_bf16 v[82:85], v[170:173], v[204:207], v[82:85]
	v_mfma_f32_16x16x32_bf16 v[70:73], v[156:159], v[222:225], v[70:73]
	v_mfma_f32_16x16x32_bf16 v[66:69], v[170:173], v[222:225], v[66:69]
	v_mfma_f32_16x16x32_bf16 v[118:121], v[166:169], v[192:195], v[118:121]
	v_mfma_f32_16x16x32_bf16 v[114:117], v[174:177], v[192:195], v[114:117]
	v_mfma_f32_16x16x32_bf16 v[102:105], v[166:169], v[200:203], v[102:105]
	v_mfma_f32_16x16x32_bf16 v[98:101], v[174:177], v[200:203], v[98:101]
	v_mfma_f32_16x16x32_bf16 v[86:89], v[166:169], v[218:221], v[86:89]
	v_mfma_f32_16x16x32_bf16 v[82:85], v[174:177], v[218:221], v[82:85]
	v_mfma_f32_16x16x32_bf16 v[70:73], v[166:169], v[226:229], v[70:73]
	v_mfma_f32_16x16x32_bf16 v[66:69], v[174:177], v[226:229], v[66:69]
	s_setprio 0
	s_barrier
	s_add_i32 s42, s42, s27
	v_lshl_add_u64 v[160:161], s[22:23], 0, v[0:1]
	s_mov_b32 m0, s42
	ds_read_b128 v[188:191], v165 offset:16384
	ds_read_b128 v[192:195], v165 offset:17408
	ds_read_b128 v[196:199], v165 offset:18432
	ds_read_b128 v[200:203], v165 offset:19456
	ds_read_b128 v[204:207], v165 offset:20480
	ds_read_b128 v[218:221], v165 offset:21504
	ds_read_b128 v[222:225], v165 offset:22528
	ds_read_b128 v[226:229], v165 offset:23552
	global_load_lds_dwordx4 v[160:161], off
	s_add_i32 m0, s42, 0x2000
	s_add_u32 s58, s22, 0x200000
	v_lshl_add_u64 v[178:179], s[22:23], 0, v[130:131]
	s_addc_u32 s59, s23, 0
	s_add_i32 s3, s3, s27
	global_load_lds_dwordx4 v[178:179], off
	v_lshl_add_u64 v[180:181], s[58:59], 0, v[0:1]
	s_mov_b32 m0, s3
	v_lshl_add_u64 v[182:183], s[24:25], 0, v[132:133]
	global_load_lds_dwordx4 v[180:181], off
	v_lshl_add_u64 v[180:181], s[58:59], 0, v[130:131]
	s_add_i32 m0, s3, 0x2000
	s_nop 0
	global_load_lds_dwordx4 v[180:181], off
	v_lshl_add_u64 v[180:181], s[24:25], 0, v[134:135]
	s_mov_b32 m0, s28
	s_nop 0
	global_load_lds_dwordx4 v[180:181], off
	s_mov_b32 m0, s29
	s_nop 0
	global_load_lds_dwordx4 v[182:183], off
	s_waitcnt vmcnt(8)
	s_waitcnt lgkmcnt(0)
	s_waitcnt lgkmcnt(0)
	v_mfma_f32_16x16x32_bf16 v[62:65], v[140:143], v[188:191], v[62:65]
	v_mfma_f32_16x16x32_bf16 v[58:61], v[148:151], v[188:191], v[58:61]
	s_barrier
	s_setprio 1
	v_mfma_f32_16x16x32_bf16 v[46:49], v[140:143], v[196:199], v[46:49]
	v_mfma_f32_16x16x32_bf16 v[42:45], v[148:151], v[196:199], v[42:45]
	v_mfma_f32_16x16x32_bf16 v[30:33], v[140:143], v[204:207], v[30:33]
	v_mfma_f32_16x16x32_bf16 v[26:29], v[148:151], v[204:207], v[26:29]
	v_mfma_f32_16x16x32_bf16 v[14:17], v[140:143], v[222:225], v[14:17]
	v_mfma_f32_16x16x32_bf16 v[10:13], v[148:151], v[222:225], v[10:13]
	v_mfma_f32_16x16x32_bf16 v[62:65], v[144:147], v[192:195], v[62:65]
	v_mfma_f32_16x16x32_bf16 v[58:61], v[152:155], v[192:195], v[58:61]
	v_mfma_f32_16x16x32_bf16 v[46:49], v[144:147], v[200:203], v[46:49]
	v_mfma_f32_16x16x32_bf16 v[42:45], v[152:155], v[200:203], v[42:45]
	v_mfma_f32_16x16x32_bf16 v[30:33], v[144:147], v[218:221], v[30:33]
	v_mfma_f32_16x16x32_bf16 v[26:29], v[152:155], v[218:221], v[26:29]
	v_mfma_f32_16x16x32_bf16 v[14:17], v[144:147], v[226:229], v[14:17]
	v_mfma_f32_16x16x32_bf16 v[10:13], v[152:155], v[226:229], v[10:13]
	v_mfma_f32_16x16x32_bf16 v[54:57], v[156:159], v[188:191], v[54:57]
	v_mfma_f32_16x16x32_bf16 v[50:53], v[170:173], v[188:191], v[50:53]
	v_mfma_f32_16x16x32_bf16 v[38:41], v[156:159], v[196:199], v[38:41]
	v_mfma_f32_16x16x32_bf16 v[34:37], v[170:173], v[196:199], v[34:37]
	v_mfma_f32_16x16x32_bf16 v[22:25], v[156:159], v[204:207], v[22:25]
	v_mfma_f32_16x16x32_bf16 v[18:21], v[170:173], v[204:207], v[18:21]
	v_mfma_f32_16x16x32_bf16 v[6:9], v[156:159], v[222:225], v[6:9]
	v_mfma_f32_16x16x32_bf16 v[2:5], v[170:173], v[222:225], v[2:5]
	v_mfma_f32_16x16x32_bf16 v[54:57], v[166:169], v[192:195], v[54:57]
	v_mfma_f32_16x16x32_bf16 v[50:53], v[174:177], v[192:195], v[50:53]
	v_mfma_f32_16x16x32_bf16 v[38:41], v[166:169], v[200:203], v[38:41]
	v_mfma_f32_16x16x32_bf16 v[34:37], v[174:177], v[200:203], v[34:37]
	v_mfma_f32_16x16x32_bf16 v[22:25], v[166:169], v[218:221], v[22:25]
	v_mfma_f32_16x16x32_bf16 v[18:21], v[174:177], v[218:221], v[18:21]
	v_mfma_f32_16x16x32_bf16 v[6:9], v[166:169], v[226:229], v[6:9]
	v_mfma_f32_16x16x32_bf16 v[2:5], v[174:177], v[226:229], v[2:5]
	s_setprio 0
	s_barrier
	s_add_i32 s3, 0, 0x18000
	s_add_i32 s42, 0, 0x1c000
	v_add_u32_e32 v152, s3, v163
	v_add_u32_e32 v174, s42, v163
	ds_read_b128 v[140:143], v152
	ds_read_b128 v[144:147], v152 offset:1024
	ds_read_b128 v[148:151], v152 offset:2048
	ds_read_b128 v[152:155], v152 offset:3072
	ds_read_b128 v[156:159], v174
	ds_read_b128 v[166:169], v174 offset:1024
	ds_read_b128 v[170:173], v174 offset:2048
	ds_read_b128 v[174:177], v174 offset:3072
	s_add_u32 s24, s24, 0x200000
	s_addc_u32 s25, s25, 0
	s_mov_b32 m0, s30
	v_lshl_add_u64 v[184:185], s[24:25], 0, v[134:135]
	ds_read_b128 v[188:191], v165 offset:32768
	ds_read_b128 v[192:195], v165 offset:33792
	ds_read_b128 v[196:199], v165 offset:34816
	ds_read_b128 v[200:203], v165 offset:35840
	ds_read_b128 v[204:207], v165 offset:36864
	ds_read_b128 v[218:221], v165 offset:37888
	ds_read_b128 v[222:225], v165 offset:38912
	ds_read_b128 v[226:229], v165 offset:39936
	global_load_lds_dwordx4 v[184:185], off
	v_lshl_add_u64 v[184:185], s[24:25], 0, v[132:133]
	s_mov_b32 m0, s31
	s_nop 0
	global_load_lds_dwordx4 v[184:185], off
	s_waitcnt vmcnt(8)
	s_waitcnt lgkmcnt(0)
	s_waitcnt lgkmcnt(0)
	v_mfma_f32_16x16x32_bf16 v[126:129], v[140:143], v[188:191], v[126:129]
	v_mfma_f32_16x16x32_bf16 v[122:125], v[148:151], v[188:191], v[122:125]
	s_barrier
	s_setprio 1
	v_mfma_f32_16x16x32_bf16 v[110:113], v[140:143], v[196:199], v[110:113]
	v_mfma_f32_16x16x32_bf16 v[106:109], v[148:151], v[196:199], v[106:109]
	v_mfma_f32_16x16x32_bf16 v[94:97], v[140:143], v[204:207], v[94:97]
	v_mfma_f32_16x16x32_bf16 v[90:93], v[148:151], v[204:207], v[90:93]
	v_mfma_f32_16x16x32_bf16 v[78:81], v[140:143], v[222:225], v[78:81]
	v_mfma_f32_16x16x32_bf16 v[74:77], v[148:151], v[222:225], v[74:77]
	v_mfma_f32_16x16x32_bf16 v[126:129], v[144:147], v[192:195], v[126:129]
	v_mfma_f32_16x16x32_bf16 v[122:125], v[152:155], v[192:195], v[122:125]
	v_mfma_f32_16x16x32_bf16 v[110:113], v[144:147], v[200:203], v[110:113]
	v_mfma_f32_16x16x32_bf16 v[106:109], v[152:155], v[200:203], v[106:109]
	v_mfma_f32_16x16x32_bf16 v[94:97], v[144:147], v[218:221], v[94:97]
	v_mfma_f32_16x16x32_bf16 v[90:93], v[152:155], v[218:221], v[90:93]
	v_mfma_f32_16x16x32_bf16 v[78:81], v[144:147], v[226:229], v[78:81]
	v_mfma_f32_16x16x32_bf16 v[74:77], v[152:155], v[226:229], v[74:77]
	v_mfma_f32_16x16x32_bf16 v[118:121], v[156:159], v[188:191], v[118:121]
	v_mfma_f32_16x16x32_bf16 v[114:117], v[170:173], v[188:191], v[114:117]
	v_mfma_f32_16x16x32_bf16 v[102:105], v[156:159], v[196:199], v[102:105]
	v_mfma_f32_16x16x32_bf16 v[98:101], v[170:173], v[196:199], v[98:101]
	v_mfma_f32_16x16x32_bf16 v[86:89], v[156:159], v[204:207], v[86:89]
	v_mfma_f32_16x16x32_bf16 v[82:85], v[170:173], v[204:207], v[82:85]
	v_mfma_f32_16x16x32_bf16 v[70:73], v[156:159], v[222:225], v[70:73]
	v_mfma_f32_16x16x32_bf16 v[66:69], v[170:173], v[222:225], v[66:69]
	v_mfma_f32_16x16x32_bf16 v[118:121], v[166:169], v[192:195], v[118:121]
	v_mfma_f32_16x16x32_bf16 v[114:117], v[174:177], v[192:195], v[114:117]
	v_mfma_f32_16x16x32_bf16 v[102:105], v[166:169], v[200:203], v[102:105]
	v_mfma_f32_16x16x32_bf16 v[98:101], v[174:177], v[200:203], v[98:101]
	v_mfma_f32_16x16x32_bf16 v[86:89], v[166:169], v[218:221], v[86:89]
	v_mfma_f32_16x16x32_bf16 v[82:85], v[174:177], v[218:221], v[82:85]
	v_mfma_f32_16x16x32_bf16 v[70:73], v[166:169], v[226:229], v[70:73]
	v_mfma_f32_16x16x32_bf16 v[66:69], v[174:177], v[226:229], v[66:69]
	s_setprio 0
	s_barrier
	s_add_i32 s3, s3, s27
	v_lshl_add_u64 v[160:161], v[160:161], 0, s[52:53]
	s_mov_b32 m0, s3
	ds_read_b128 v[188:191], v165 offset:49152
	ds_read_b128 v[192:195], v165 offset:50176
	ds_read_b128 v[196:199], v165 offset:51200
	ds_read_b128 v[200:203], v165 offset:52224
	ds_read_b128 v[204:207], v165 offset:53248
	ds_read_b128 v[218:221], v165 offset:54272
	ds_read_b128 v[222:225], v165 offset:55296
	ds_read_b128 v[226:229], v165 offset:56320
	global_load_lds_dwordx4 v[160:161], off
	s_add_i32 m0, s3, 0x2000
	s_add_u32 s22, s22, 0x200080
	v_lshl_add_u64 v[160:161], v[178:179], 0, s[52:53]
	s_addc_u32 s23, s23, 0
	s_add_i32 s3, s42, s27
	global_load_lds_dwordx4 v[160:161], off
	v_lshl_add_u64 v[160:161], s[22:23], 0, v[0:1]
	s_mov_b32 m0, s3
	s_nop 0
	global_load_lds_dwordx4 v[160:161], off
	v_lshl_add_u64 v[160:161], s[22:23], 0, v[130:131]
	s_add_i32 m0, s3, 0x2000
	s_nop 0
	global_load_lds_dwordx4 v[160:161], off
	v_lshl_add_u64 v[160:161], v[180:181], 0, s[52:53]
	s_mov_b32 m0, s34
	s_nop 0
	global_load_lds_dwordx4 v[160:161], off
	v_lshl_add_u64 v[160:161], v[182:183], 0, s[52:53]
	s_mov_b32 m0, s35
	s_nop 0
	global_load_lds_dwordx4 v[160:161], off
	s_waitcnt vmcnt(8)
	s_waitcnt lgkmcnt(0)
	s_waitcnt lgkmcnt(0)
	v_mfma_f32_16x16x32_bf16 v[62:65], v[140:143], v[188:191], v[62:65]
	v_mfma_f32_16x16x32_bf16 v[58:61], v[148:151], v[188:191], v[58:61]
	s_barrier
	s_setprio 1
	v_mfma_f32_16x16x32_bf16 v[46:49], v[140:143], v[196:199], v[46:49]
	v_mfma_f32_16x16x32_bf16 v[42:45], v[148:151], v[196:199], v[42:45]
	v_mfma_f32_16x16x32_bf16 v[30:33], v[140:143], v[204:207], v[30:33]
	v_mfma_f32_16x16x32_bf16 v[26:29], v[148:151], v[204:207], v[26:29]
	v_mfma_f32_16x16x32_bf16 v[14:17], v[140:143], v[222:225], v[14:17]
	v_mfma_f32_16x16x32_bf16 v[10:13], v[148:151], v[222:225], v[10:13]
	v_mfma_f32_16x16x32_bf16 v[62:65], v[144:147], v[192:195], v[62:65]
	v_mfma_f32_16x16x32_bf16 v[58:61], v[152:155], v[192:195], v[58:61]
	v_mfma_f32_16x16x32_bf16 v[46:49], v[144:147], v[200:203], v[46:49]
	v_mfma_f32_16x16x32_bf16 v[42:45], v[152:155], v[200:203], v[42:45]
	v_mfma_f32_16x16x32_bf16 v[30:33], v[144:147], v[218:221], v[30:33]
	v_mfma_f32_16x16x32_bf16 v[26:29], v[152:155], v[218:221], v[26:29]
	v_mfma_f32_16x16x32_bf16 v[14:17], v[144:147], v[226:229], v[14:17]
	v_mfma_f32_16x16x32_bf16 v[10:13], v[152:155], v[226:229], v[10:13]
	v_mfma_f32_16x16x32_bf16 v[54:57], v[156:159], v[188:191], v[54:57]
	v_mfma_f32_16x16x32_bf16 v[50:53], v[170:173], v[188:191], v[50:53]
	v_mfma_f32_16x16x32_bf16 v[38:41], v[156:159], v[196:199], v[38:41]
	v_mfma_f32_16x16x32_bf16 v[34:37], v[170:173], v[196:199], v[34:37]
	v_mfma_f32_16x16x32_bf16 v[22:25], v[156:159], v[204:207], v[22:25]
	v_mfma_f32_16x16x32_bf16 v[18:21], v[170:173], v[204:207], v[18:21]
	v_mfma_f32_16x16x32_bf16 v[6:9], v[156:159], v[222:225], v[6:9]
	v_mfma_f32_16x16x32_bf16 v[2:5], v[170:173], v[222:225], v[2:5]
	v_mfma_f32_16x16x32_bf16 v[54:57], v[166:169], v[192:195], v[54:57]
	v_mfma_f32_16x16x32_bf16 v[50:53], v[174:177], v[192:195], v[50:53]
	v_mfma_f32_16x16x32_bf16 v[38:41], v[166:169], v[200:203], v[38:41]
	v_mfma_f32_16x16x32_bf16 v[34:37], v[174:177], v[200:203], v[34:37]
	v_mfma_f32_16x16x32_bf16 v[22:25], v[166:169], v[218:221], v[22:25]
	v_mfma_f32_16x16x32_bf16 v[18:21], v[174:177], v[218:221], v[18:21]
	v_mfma_f32_16x16x32_bf16 v[6:9], v[166:169], v[226:229], v[6:9]
	v_mfma_f32_16x16x32_bf16 v[2:5], v[174:177], v[226:229], v[2:5]
	s_setprio 0
	s_barrier
	s_add_i32 s57, s57, 2
	s_add_u32 s20, s20, 0x100
	s_addc_u32 s21, s21, 0
	s_add_u32 s47, s47, 0x100
	s_addc_u32 s56, s56, 0
	s_cmpk_gt_u32 s57, 0x7d
	s_cbranch_scc0 .LBB0_1024
	s_and_b64 vcc, exec, s[10:11]
	s_mov_b32 s45, 0xa000
	s_cbranch_vccz .LBB0_1027
	s_barrier

.LBB0_1046:
	s_add_u32 s3, s18, 0xffe00080
	s_addc_u32 s20, s19, -1
	s_add_i32 s42, 0, 0x10000
	s_cmpk_eq_i32 s47, 0x7c
	s_cselect_b32 s23, s13, s20
	s_cselect_b32 s22, s41, s3
	s_cselect_b32 s21, s11, s46
	s_cselect_b32 s20, s44, s45
	s_add_i32 s3, 0, 0x14000
	v_add_u32_e32 v152, s42, v163
	v_add_u32_e32 v160, s3, v163
	ds_read_b128 v[140:143], v152
	ds_read_b128 v[144:147], v152 offset:1024
	ds_read_b128 v[148:151], v152 offset:2048
	ds_read_b128 v[152:155], v152 offset:3072
	ds_read_b128 v[156:159], v160
	ds_read_b128 v[166:169], v160 offset:1024
	ds_read_b128 v[170:173], v160 offset:2048
	ds_read_b128 v[174:177], v160 offset:3072
	v_lshl_add_u64 v[160:161], s[18:19], 0, v[136:137]
	s_add_i32 m0, s25, 0xc000
	ds_read_b128 v[188:191], v165
	ds_read_b128 v[192:195], v165 offset:1024
	ds_read_b128 v[196:199], v165 offset:2048
	ds_read_b128 v[200:203], v165 offset:3072
	ds_read_b128 v[204:207], v165 offset:4096
	ds_read_b128 v[218:221], v165 offset:5120
	ds_read_b128 v[222:225], v165 offset:6144
	ds_read_b128 v[226:229], v165 offset:7168
	global_load_lds_dwordx4 v[160:161], off
	v_lshl_add_u64 v[160:161], s[18:19], 0, v[138:139]
	s_add_i32 m0, s25, 0xe000
	s_nop 0
	global_load_lds_dwordx4 v[160:161], off
	s_waitcnt vmcnt(8)
	s_waitcnt lgkmcnt(0)
	s_waitcnt lgkmcnt(0)
	v_mfma_f32_16x16x32_bf16 v[126:129], v[140:143], v[188:191], v[126:129]
	v_mfma_f32_16x16x32_bf16 v[122:125], v[148:151], v[188:191], v[122:125]
	s_barrier
	s_setprio 1
	v_mfma_f32_16x16x32_bf16 v[110:113], v[140:143], v[196:199], v[110:113]
	v_mfma_f32_16x16x32_bf16 v[106:109], v[148:151], v[196:199], v[106:109]
	v_mfma_f32_16x16x32_bf16 v[94:97], v[140:143], v[204:207], v[94:97]
	v_mfma_f32_16x16x32_bf16 v[90:93], v[148:151], v[204:207], v[90:93]
	v_mfma_f32_16x16x32_bf16 v[78:81], v[140:143], v[222:225], v[78:81]
	v_mfma_f32_16x16x32_bf16 v[74:77], v[148:151], v[222:225], v[74:77]
	v_mfma_f32_16x16x32_bf16 v[126:129], v[144:147], v[192:195], v[126:129]
	v_mfma_f32_16x16x32_bf16 v[122:125], v[152:155], v[192:195], v[122:125]
	v_mfma_f32_16x16x32_bf16 v[110:113], v[144:147], v[200:203], v[110:113]
	v_mfma_f32_16x16x32_bf16 v[106:109], v[152:155], v[200:203], v[106:109]
	v_mfma_f32_16x16x32_bf16 v[94:97], v[144:147], v[218:221], v[94:97]
	v_mfma_f32_16x16x32_bf16 v[90:93], v[152:155], v[218:221], v[90:93]
	v_mfma_f32_16x16x32_bf16 v[78:81], v[144:147], v[226:229], v[78:81]
	v_mfma_f32_16x16x32_bf16 v[74:77], v[152:155], v[226:229], v[74:77]
	v_mfma_f32_16x16x32_bf16 v[118:121], v[156:159], v[188:191], v[118:121]
	v_mfma_f32_16x16x32_bf16 v[114:117], v[170:173], v[188:191], v[114:117]
	v_mfma_f32_16x16x32_bf16 v[102:105], v[156:159], v[196:199], v[102:105]
	v_mfma_f32_16x16x32_bf16 v[98:101], v[170:173], v[196:199], v[98:101]
	v_mfma_f32_16x16x32_bf16 v[86:89], v[156:159], v[204:207], v[86:89]
	v_mfma_f32_16x16x32_bf16 v[82:85], v[170:173], v[204:207], v[82:85]
	v_mfma_f32_16x16x32_bf16 v[70:73], v[156:159], v[222:225], v[70:73]
	v_mfma_f32_16x16x32_bf16 v[66:69], v[170:173], v[222:225], v[66:69]
	v_mfma_f32_16x16x32_bf16 v[118:121], v[166:169], v[192:195], v[118:121]
	v_mfma_f32_16x16x32_bf16 v[114:117], v[174:177], v[192:195], v[114:117]
	v_mfma_f32_16x16x32_bf16 v[102:105], v[166:169], v[200:203], v[102:105]
	v_mfma_f32_16x16x32_bf16 v[98:101], v[174:177], v[200:203], v[98:101]
	v_mfma_f32_16x16x32_bf16 v[86:89], v[166:169], v[218:221], v[86:89]
	v_mfma_f32_16x16x32_bf16 v[82:85], v[174:177], v[218:221], v[82:85]
	v_mfma_f32_16x16x32_bf16 v[70:73], v[166:169], v[226:229], v[70:73]
	v_mfma_f32_16x16x32_bf16 v[66:69], v[174:177], v[226:229], v[66:69]
	s_setprio 0
	s_barrier
	s_add_i32 s42, s42, s24
	v_lshl_add_u64 v[160:161], s[20:21], 0, v[0:1]
	s_mov_b32 m0, s42
	ds_read_b128 v[188:191], v165 offset:16384
	ds_read_b128 v[192:195], v165 offset:17408
	ds_read_b128 v[196:199], v165 offset:18432
	ds_read_b128 v[200:203], v165 offset:19456
	ds_read_b128 v[204:207], v165 offset:20480
	ds_read_b128 v[218:221], v165 offset:21504
	ds_read_b128 v[222:225], v165 offset:22528
	ds_read_b128 v[226:229], v165 offset:23552
	global_load_lds_dwordx4 v[160:161], off
	s_add_i32 m0, s42, 0x2000
	s_add_u32 s56, s20, 0x200000
	v_lshl_add_u64 v[178:179], s[20:21], 0, v[130:131]
	s_addc_u32 s57, s21, 0
	s_add_i32 s3, s3, s24
	global_load_lds_dwordx4 v[178:179], off
	v_lshl_add_u64 v[180:181], s[56:57], 0, v[0:1]
	s_mov_b32 m0, s3
	v_lshl_add_u64 v[182:183], s[22:23], 0, v[132:133]
	global_load_lds_dwordx4 v[180:181], off
	v_lshl_add_u64 v[180:181], s[56:57], 0, v[130:131]
	s_add_i32 m0, s3, 0x2000
	s_nop 0
	global_load_lds_dwordx4 v[180:181], off
	v_lshl_add_u64 v[180:181], s[22:23], 0, v[134:135]
	s_mov_b32 m0, s25
	s_nop 0
	global_load_lds_dwordx4 v[180:181], off
	s_mov_b32 m0, s27
	s_nop 0
	global_load_lds_dwordx4 v[182:183], off
	s_waitcnt vmcnt(8)
	s_waitcnt lgkmcnt(0)
	s_waitcnt lgkmcnt(0)
	v_mfma_f32_16x16x32_bf16 v[62:65], v[140:143], v[188:191], v[62:65]
	v_mfma_f32_16x16x32_bf16 v[58:61], v[148:151], v[188:191], v[58:61]
	s_barrier
	s_setprio 1
	v_mfma_f32_16x16x32_bf16 v[46:49], v[140:143], v[196:199], v[46:49]
	v_mfma_f32_16x16x32_bf16 v[42:45], v[148:151], v[196:199], v[42:45]
	v_mfma_f32_16x16x32_bf16 v[30:33], v[140:143], v[204:207], v[30:33]
	v_mfma_f32_16x16x32_bf16 v[26:29], v[148:151], v[204:207], v[26:29]
	v_mfma_f32_16x16x32_bf16 v[14:17], v[140:143], v[222:225], v[14:17]
	v_mfma_f32_16x16x32_bf16 v[10:13], v[148:151], v[222:225], v[10:13]
	v_mfma_f32_16x16x32_bf16 v[62:65], v[144:147], v[192:195], v[62:65]
	v_mfma_f32_16x16x32_bf16 v[58:61], v[152:155], v[192:195], v[58:61]
	v_mfma_f32_16x16x32_bf16 v[46:49], v[144:147], v[200:203], v[46:49]
	v_mfma_f32_16x16x32_bf16 v[42:45], v[152:155], v[200:203], v[42:45]
	v_mfma_f32_16x16x32_bf16 v[30:33], v[144:147], v[218:221], v[30:33]
	v_mfma_f32_16x16x32_bf16 v[26:29], v[152:155], v[218:221], v[26:29]
	v_mfma_f32_16x16x32_bf16 v[14:17], v[144:147], v[226:229], v[14:17]
	v_mfma_f32_16x16x32_bf16 v[10:13], v[152:155], v[226:229], v[10:13]
	v_mfma_f32_16x16x32_bf16 v[54:57], v[156:159], v[188:191], v[54:57]
	v_mfma_f32_16x16x32_bf16 v[50:53], v[170:173], v[188:191], v[50:53]
	v_mfma_f32_16x16x32_bf16 v[38:41], v[156:159], v[196:199], v[38:41]
	v_mfma_f32_16x16x32_bf16 v[34:37], v[170:173], v[196:199], v[34:37]
	v_mfma_f32_16x16x32_bf16 v[22:25], v[156:159], v[204:207], v[22:25]
	v_mfma_f32_16x16x32_bf16 v[18:21], v[170:173], v[204:207], v[18:21]
	v_mfma_f32_16x16x32_bf16 v[6:9], v[156:159], v[222:225], v[6:9]
	v_mfma_f32_16x16x32_bf16 v[2:5], v[170:173], v[222:225], v[2:5]
	v_mfma_f32_16x16x32_bf16 v[54:57], v[166:169], v[192:195], v[54:57]
	v_mfma_f32_16x16x32_bf16 v[50:53], v[174:177], v[192:195], v[50:53]
	v_mfma_f32_16x16x32_bf16 v[38:41], v[166:169], v[200:203], v[38:41]
	v_mfma_f32_16x16x32_bf16 v[34:37], v[174:177], v[200:203], v[34:37]
	v_mfma_f32_16x16x32_bf16 v[22:25], v[166:169], v[218:221], v[22:25]
	v_mfma_f32_16x16x32_bf16 v[18:21], v[174:177], v[218:221], v[18:21]
	v_mfma_f32_16x16x32_bf16 v[6:9], v[166:169], v[226:229], v[6:9]
	v_mfma_f32_16x16x32_bf16 v[2:5], v[174:177], v[226:229], v[2:5]
	s_setprio 0
	s_barrier
	s_add_i32 s3, 0, 0x18000
	s_add_i32 s42, 0, 0x1c000
	v_add_u32_e32 v152, s3, v163
	v_add_u32_e32 v174, s42, v163
	ds_read_b128 v[140:143], v152
	ds_read_b128 v[144:147], v152 offset:1024
	ds_read_b128 v[148:151], v152 offset:2048
	ds_read_b128 v[152:155], v152 offset:3072
	ds_read_b128 v[156:159], v174
	ds_read_b128 v[166:169], v174 offset:1024
	ds_read_b128 v[170:173], v174 offset:2048
	ds_read_b128 v[174:177], v174 offset:3072
	s_add_u32 s22, s22, 0x200000
	s_addc_u32 s23, s23, 0
	s_mov_b32 m0, s28
	v_lshl_add_u64 v[184:185], s[22:23], 0, v[134:135]
	ds_read_b128 v[188:191], v165 offset:32768
	ds_read_b128 v[192:195], v165 offset:33792
	ds_read_b128 v[196:199], v165 offset:34816
	ds_read_b128 v[200:203], v165 offset:35840
	ds_read_b128 v[204:207], v165 offset:36864
	ds_read_b128 v[218:221], v165 offset:37888
	ds_read_b128 v[222:225], v165 offset:38912
	ds_read_b128 v[226:229], v165 offset:39936
	global_load_lds_dwordx4 v[184:185], off
	v_lshl_add_u64 v[184:185], s[22:23], 0, v[132:133]
	s_mov_b32 m0, s29
	s_nop 0
	global_load_lds_dwordx4 v[184:185], off
	s_waitcnt vmcnt(8)
	s_waitcnt lgkmcnt(0)
	s_waitcnt lgkmcnt(0)
	v_mfma_f32_16x16x32_bf16 v[126:129], v[140:143], v[188:191], v[126:129]
	v_mfma_f32_16x16x32_bf16 v[122:125], v[148:151], v[188:191], v[122:125]
	s_barrier
	s_setprio 1
	v_mfma_f32_16x16x32_bf16 v[110:113], v[140:143], v[196:199], v[110:113]
	v_mfma_f32_16x16x32_bf16 v[106:109], v[148:151], v[196:199], v[106:109]
	v_mfma_f32_16x16x32_bf16 v[94:97], v[140:143], v[204:207], v[94:97]
	v_mfma_f32_16x16x32_bf16 v[90:93], v[148:151], v[204:207], v[90:93]
	v_mfma_f32_16x16x32_bf16 v[78:81], v[140:143], v[222:225], v[78:81]
	v_mfma_f32_16x16x32_bf16 v[74:77], v[148:151], v[222:225], v[74:77]
	v_mfma_f32_16x16x32_bf16 v[126:129], v[144:147], v[192:195], v[126:129]
	v_mfma_f32_16x16x32_bf16 v[122:125], v[152:155], v[192:195], v[122:125]
	v_mfma_f32_16x16x32_bf16 v[110:113], v[144:147], v[200:203], v[110:113]
	v_mfma_f32_16x16x32_bf16 v[106:109], v[152:155], v[200:203], v[106:109]
	v_mfma_f32_16x16x32_bf16 v[94:97], v[144:147], v[218:221], v[94:97]
	v_mfma_f32_16x16x32_bf16 v[90:93], v[152:155], v[218:221], v[90:93]
	v_mfma_f32_16x16x32_bf16 v[78:81], v[144:147], v[226:229], v[78:81]
	v_mfma_f32_16x16x32_bf16 v[74:77], v[152:155], v[226:229], v[74:77]
	v_mfma_f32_16x16x32_bf16 v[118:121], v[156:159], v[188:191], v[118:121]
	v_mfma_f32_16x16x32_bf16 v[114:117], v[170:173], v[188:191], v[114:117]
	v_mfma_f32_16x16x32_bf16 v[102:105], v[156:159], v[196:199], v[102:105]
	v_mfma_f32_16x16x32_bf16 v[98:101], v[170:173], v[196:199], v[98:101]
	v_mfma_f32_16x16x32_bf16 v[86:89], v[156:159], v[204:207], v[86:89]
	v_mfma_f32_16x16x32_bf16 v[82:85], v[170:173], v[204:207], v[82:85]
	v_mfma_f32_16x16x32_bf16 v[70:73], v[156:159], v[222:225], v[70:73]
	v_mfma_f32_16x16x32_bf16 v[66:69], v[170:173], v[222:225], v[66:69]
	v_mfma_f32_16x16x32_bf16 v[118:121], v[166:169], v[192:195], v[118:121]
	v_mfma_f32_16x16x32_bf16 v[114:117], v[174:177], v[192:195], v[114:117]
	v_mfma_f32_16x16x32_bf16 v[102:105], v[166:169], v[200:203], v[102:105]
	v_mfma_f32_16x16x32_bf16 v[98:101], v[174:177], v[200:203], v[98:101]
	v_mfma_f32_16x16x32_bf16 v[86:89], v[166:169], v[218:221], v[86:89]
	v_mfma_f32_16x16x32_bf16 v[82:85], v[174:177], v[218:221], v[82:85]
	v_mfma_f32_16x16x32_bf16 v[70:73], v[166:169], v[226:229], v[70:73]
	v_mfma_f32_16x16x32_bf16 v[66:69], v[174:177], v[226:229], v[66:69]
	s_setprio 0
	s_barrier
	s_add_i32 s3, s3, s24
	v_lshl_add_u64 v[160:161], v[160:161], 0, s[52:53]
	s_mov_b32 m0, s3
	ds_read_b128 v[188:191], v165 offset:49152
	ds_read_b128 v[192:195], v165 offset:50176
	ds_read_b128 v[196:199], v165 offset:51200
	ds_read_b128 v[200:203], v165 offset:52224
	ds_read_b128 v[204:207], v165 offset:53248
	ds_read_b128 v[218:221], v165 offset:54272
	ds_read_b128 v[222:225], v165 offset:55296
	ds_read_b128 v[226:229], v165 offset:56320
	global_load_lds_dwordx4 v[160:161], off
	s_add_i32 m0, s3, 0x2000
	s_add_u32 s20, s20, 0x200080
	v_lshl_add_u64 v[160:161], v[178:179], 0, s[52:53]
	s_addc_u32 s21, s21, 0
	s_add_i32 s3, s42, s24
	global_load_lds_dwordx4 v[160:161], off
	v_lshl_add_u64 v[160:161], s[20:21], 0, v[0:1]
	s_mov_b32 m0, s3
	s_nop 0
	global_load_lds_dwordx4 v[160:161], off
	v_lshl_add_u64 v[160:161], s[20:21], 0, v[130:131]
	s_add_i32 m0, s3, 0x2000
	s_nop 0
	global_load_lds_dwordx4 v[160:161], off
	v_lshl_add_u64 v[160:161], v[180:181], 0, s[52:53]
	s_mov_b32 m0, s30
	s_nop 0
	global_load_lds_dwordx4 v[160:161], off
	v_lshl_add_u64 v[160:161], v[182:183], 0, s[52:53]
	s_mov_b32 m0, s31
	s_nop 0
	global_load_lds_dwordx4 v[160:161], off
	s_waitcnt vmcnt(8)
	s_waitcnt lgkmcnt(0)
	s_waitcnt lgkmcnt(0)
	v_mfma_f32_16x16x32_bf16 v[62:65], v[140:143], v[188:191], v[62:65]
	v_mfma_f32_16x16x32_bf16 v[58:61], v[148:151], v[188:191], v[58:61]
	s_barrier
	s_setprio 1
	v_mfma_f32_16x16x32_bf16 v[46:49], v[140:143], v[196:199], v[46:49]
	v_mfma_f32_16x16x32_bf16 v[42:45], v[148:151], v[196:199], v[42:45]
	v_mfma_f32_16x16x32_bf16 v[30:33], v[140:143], v[204:207], v[30:33]
	v_mfma_f32_16x16x32_bf16 v[26:29], v[148:151], v[204:207], v[26:29]
	v_mfma_f32_16x16x32_bf16 v[14:17], v[140:143], v[222:225], v[14:17]
	v_mfma_f32_16x16x32_bf16 v[10:13], v[148:151], v[222:225], v[10:13]
	v_mfma_f32_16x16x32_bf16 v[62:65], v[144:147], v[192:195], v[62:65]
	v_mfma_f32_16x16x32_bf16 v[58:61], v[152:155], v[192:195], v[58:61]
	v_mfma_f32_16x16x32_bf16 v[46:49], v[144:147], v[200:203], v[46:49]
	v_mfma_f32_16x16x32_bf16 v[42:45], v[152:155], v[200:203], v[42:45]
	v_mfma_f32_16x16x32_bf16 v[30:33], v[144:147], v[218:221], v[30:33]
	v_mfma_f32_16x16x32_bf16 v[26:29], v[152:155], v[218:221], v[26:29]
	v_mfma_f32_16x16x32_bf16 v[14:17], v[144:147], v[226:229], v[14:17]
	v_mfma_f32_16x16x32_bf16 v[10:13], v[152:155], v[226:229], v[10:13]
	v_mfma_f32_16x16x32_bf16 v[54:57], v[156:159], v[188:191], v[54:57]
	v_mfma_f32_16x16x32_bf16 v[50:53], v[170:173], v[188:191], v[50:53]
	v_mfma_f32_16x16x32_bf16 v[38:41], v[156:159], v[196:199], v[38:41]
	v_mfma_f32_16x16x32_bf16 v[34:37], v[170:173], v[196:199], v[34:37]
	v_mfma_f32_16x16x32_bf16 v[22:25], v[156:159], v[204:207], v[22:25]
	v_mfma_f32_16x16x32_bf16 v[18:21], v[170:173], v[204:207], v[18:21]
	v_mfma_f32_16x16x32_bf16 v[6:9], v[156:159], v[222:225], v[6:9]
	v_mfma_f32_16x16x32_bf16 v[2:5], v[170:173], v[222:225], v[2:5]
	v_mfma_f32_16x16x32_bf16 v[54:57], v[166:169], v[192:195], v[54:57]
	v_mfma_f32_16x16x32_bf16 v[50:53], v[174:177], v[192:195], v[50:53]
	v_mfma_f32_16x16x32_bf16 v[38:41], v[166:169], v[200:203], v[38:41]
	v_mfma_f32_16x16x32_bf16 v[34:37], v[174:177], v[200:203], v[34:37]
	v_mfma_f32_16x16x32_bf16 v[22:25], v[166:169], v[218:221], v[22:25]
	v_mfma_f32_16x16x32_bf16 v[18:21], v[174:177], v[218:221], v[18:21]
	v_mfma_f32_16x16x32_bf16 v[6:9], v[166:169], v[226:229], v[6:9]
	v_mfma_f32_16x16x32_bf16 v[2:5], v[174:177], v[226:229], v[2:5]
	s_setprio 0
	s_barrier
	s_add_i32 s47, s47, 2
	s_add_u32 s18, s18, 0x100
	s_addc_u32 s19, s19, 0
	s_add_u32 s45, s45, 0x100
	s_addc_u32 s46, s46, 0
	s_cmpk_gt_u32 s47, 0x7d
	s_cbranch_scc0 .LBB0_1046
	s_and_b64 vcc, exec, s[8:9]
	s_movk_i32 s41, 0x6000
	s_mov_b32 s44, 0x8000
	s_mov_b32 s45, 0xa000
	s_cbranch_vccz .LBB0_1049
	s_barrier
